# fix of a latent RAW in the merged loops: prologue wait vmcnt(4)->vmcnt(2) so the hoisted B1 read of SB(0,1) sees the lagging half's pieces; plus immediate-offset B reads
# speedup vs baseline: 1.0029x; 1.0029x over previous
.LBB0_62:
	v_lshrrev_b32_e32 v16, 1, v5
	v_and_b32_e32 v16, 24, v16
	v_and_b32_e32 v7, 15, v5
	v_lshlrev_b32_e32 v17, 1, v16
	v_lshlrev_b32_e32 v5, 2, v5
	s_sext_i32_i16 s71, s22
	v_lshl_or_b32 v138, s26, 6, v7
	v_lshl_or_b32 v7, v7, 6, v17
	s_lshl_b32 s22, s26, 13
	v_and_b32_e32 v5, 32, v5
	v_lshl_add_u64 v[8:9], s[42:43], 0, v[184:185]
	v_mov_b32_e32 v129, v185
	v_bitop3_b32 v139, v7, s22, v5 bitop3:0xde
	s_lshl_b32 s22, s23, 5
	s_add_i32 s33, s50, 0x18000
	v_lshl_add_u64 v[10:11], s[42:43], 0, v[128:129]
	v_mov_b32_e32 v133, v185
	s_and_b32 s26, s22, 0x60
	v_lshl_add_u64 v[8:9], v[8:9], 0, s[24:25]
	s_mov_b32 m0, s33
	s_add_i32 s61, s50, 0x1a000
	v_lshl_add_u64 v[12:13], s[40:41], 0, v[132:133]
	v_mov_b32_e32 v131, v185
	s_lshl_b32 s22, s26, 7
	s_waitcnt vmcnt(2)
	s_barrier
	global_load_lds_dwordx4 v[8:9], off
	v_lshl_add_u64 v[8:9], v[10:11], 0, s[24:25]
	s_mov_b32 m0, s61
	s_add_i32 s62, s50, 0x8000
	s_add_i32 s63, s50, 0xa000
	v_lshl_add_u64 v[14:15], s[40:41], 0, v[130:131]
	v_bitop3_b32 v140, v7, s22, v5 bitop3:0xde
	global_load_lds_dwordx4 v[8:9], off
	v_lshl_add_u64 v[8:9], v[12:13], 0, s[24:25]
	s_mov_b32 m0, s62
	s_add_u32 s22, s42, 0x40080
	global_load_lds_dwordx4 v[8:9], off
	v_lshl_add_u64 v[8:9], v[14:15], 0, s[24:25]
	s_mov_b32 m0, s63
	s_addc_u32 s23, s43, 0
	s_add_i32 s64, s50, 0x1c000
	global_load_lds_dwordx4 v[8:9], off
	v_lshl_add_u64 v[8:9], s[22:23], 0, v[184:185]
	s_mov_b32 m0, s64
	s_add_i32 s65, s50, 0x1e000
	global_load_lds_dwordx4 v[8:9], off
	v_lshl_add_u64 v[8:9], s[22:23], 0, v[128:129]
	s_mov_b32 m0, s65
	v_lshlrev_b32_e32 v5, 14, v4
	global_load_lds_dwordx4 v[8:9], off
	v_and_b32_e32 v5, 0xffff8000, v5
	v_lshl_add_u32 v3, v3, 11, v5
	v_and_b32_e32 v4, 1, v4
	v_lshl_or_b32 v3, v4, 6, v3
	v_lshl_add_u32 v134, v6, 1, v3
	v_lshlrev_b32_e32 v3, 14, v0
	v_and_b32_e32 v3, 0xffff8000, v3
	s_waitcnt vmcnt(6)
	v_lshl_add_u32 v1, v1, 11, v3
	v_and_b32_e32 v0, 1, v0
	v_lshl_or_b32 v0, v0, 6, v1
	v_or_b32_e32 v141, s26, v16
	v_mov_b32_e32 v135, v185
	v_lshl_add_u32 v136, v2, 1, v0
	v_mov_b32_e32 v137, v185
	s_mov_b32 s68, 0
	s_add_i32 s69, s50, 0xc000
	s_add_i32 s70, s50, 0xe000
	s_barrier

.LBB0_65:
	s_ashr_i32 s31, s30, 31
	v_readlane_b32 s4, v253, 16
	s_lshl_b64 s[26:27], s[30:31], 19
	v_readlane_b32 s6, v253, 18
	v_readlane_b32 s7, v253, 19
	s_add_u32 s34, s6, s26
	s_addc_u32 s35, s7, s27
	s_cmp_eq_u32 s101, 2
	s_cselect_b32 s26, 0x40000, 0
	s_add_u32 s34, s34, s26
	s_addc_u32 s35, s35, 0
	s_and_b64 s[26:27], s[44:45], exec
	s_cselect_b32 s31, s35, s41
	s_cselect_b32 s80, s34, s40
	s_ashr_i32 s29, s28, 31
	s_lshl_b64 s[26:27], s[28:29], 19
	s_add_u32 s36, s48, s26
	s_addc_u32 s37, s49, s27
	s_and_b64 s[26:27], s[44:45], exec
	s_cselect_b32 s29, s37, s43
	s_cselect_b32 vcc_lo, s36, s42
	s_add_u32 s40, s40, 0x40080
	s_addc_u32 s41, s41, 0
	s_add_u32 s26, s42, 0x100
	v_mov_b32_e32 v0, 0
	s_addc_u32 s27, s43, 0
	s_mov_b32 s96, -2
	v_mov_b32_e32 v1, v0
	v_mov_b32_e32 v2, v0
	v_mov_b32_e32 v3, v0
	v_mov_b32_e32 v8, v0
	v_mov_b32_e32 v9, v0
	v_mov_b32_e32 v10, v0
	v_mov_b32_e32 v11, v0
	v_mov_b32_e32 v16, v0
	v_mov_b32_e32 v17, v0
	v_mov_b32_e32 v18, v0
	v_mov_b32_e32 v19, v0
	v_mov_b32_e32 v24, v0
	v_mov_b32_e32 v25, v0
	v_mov_b32_e32 v26, v0
	v_mov_b32_e32 v27, v0
	v_mov_b32_e32 v32, v0
	v_mov_b32_e32 v33, v0
	v_mov_b32_e32 v34, v0
	v_mov_b32_e32 v35, v0
	v_mov_b32_e32 v40, v0
	v_mov_b32_e32 v41, v0
	v_mov_b32_e32 v42, v0
	v_mov_b32_e32 v43, v0
	v_mov_b32_e32 v48, v0
	v_mov_b32_e32 v49, v0
	v_mov_b32_e32 v50, v0
	v_mov_b32_e32 v51, v0
	v_mov_b32_e32 v56, v0
	v_mov_b32_e32 v57, v0
	v_mov_b32_e32 v58, v0
	v_mov_b32_e32 v59, v0
	v_mov_b32_e32 v4, v0
	v_mov_b32_e32 v5, v0
	v_mov_b32_e32 v6, v0
	v_mov_b32_e32 v7, v0
	v_mov_b32_e32 v12, v0
	v_mov_b32_e32 v13, v0
	v_mov_b32_e32 v14, v0
	v_mov_b32_e32 v15, v0
	v_mov_b32_e32 v20, v0
	v_mov_b32_e32 v21, v0
	v_mov_b32_e32 v22, v0
	v_mov_b32_e32 v23, v0
	v_mov_b32_e32 v28, v0
	v_mov_b32_e32 v29, v0
	v_mov_b32_e32 v30, v0
	v_mov_b32_e32 v31, v0
	v_mov_b32_e32 v36, v0
	v_mov_b32_e32 v37, v0
	v_mov_b32_e32 v38, v0
	v_mov_b32_e32 v39, v0
	v_mov_b32_e32 v44, v0
	v_mov_b32_e32 v45, v0
	v_mov_b32_e32 v46, v0
	v_mov_b32_e32 v47, v0
	v_mov_b32_e32 v52, v0
	v_mov_b32_e32 v53, v0
	v_mov_b32_e32 v54, v0
	v_mov_b32_e32 v55, v0
	v_mov_b32_e32 v60, v0
	v_mov_b32_e32 v61, v0
	v_mov_b32_e32 v62, v0
	v_mov_b32_e32 v63, v0
	v_mov_b32_e32 v64, v0
	v_mov_b32_e32 v65, v0
	v_mov_b32_e32 v66, v0
	v_mov_b32_e32 v67, v0
	v_mov_b32_e32 v72, v0
	v_mov_b32_e32 v73, v0
	v_mov_b32_e32 v74, v0
	v_mov_b32_e32 v75, v0
	v_mov_b32_e32 v80, v0
	v_mov_b32_e32 v81, v0
	v_mov_b32_e32 v82, v0
	v_mov_b32_e32 v83, v0
	v_mov_b32_e32 v88, v0
	v_mov_b32_e32 v89, v0
	v_mov_b32_e32 v90, v0
	v_mov_b32_e32 v91, v0
	v_mov_b32_e32 v96, v0
	v_mov_b32_e32 v97, v0
	v_mov_b32_e32 v98, v0
	v_mov_b32_e32 v99, v0
	v_mov_b32_e32 v104, v0
	v_mov_b32_e32 v105, v0
	v_mov_b32_e32 v106, v0
	v_mov_b32_e32 v107, v0
	v_mov_b32_e32 v112, v0
	v_mov_b32_e32 v113, v0
	v_mov_b32_e32 v114, v0
	v_mov_b32_e32 v115, v0
	v_mov_b32_e32 v120, v0
	v_mov_b32_e32 v121, v0
	v_mov_b32_e32 v122, v0
	v_mov_b32_e32 v123, v0
	v_mov_b32_e32 v68, v0
	v_mov_b32_e32 v69, v0
	v_mov_b32_e32 v70, v0
	v_mov_b32_e32 v71, v0
	v_mov_b32_e32 v76, v0
	v_mov_b32_e32 v77, v0
	v_mov_b32_e32 v78, v0
	v_mov_b32_e32 v79, v0
	v_mov_b32_e32 v84, v0
	v_mov_b32_e32 v85, v0
	v_mov_b32_e32 v86, v0
	v_mov_b32_e32 v87, v0
	v_mov_b32_e32 v92, v0
	v_mov_b32_e32 v93, v0
	v_mov_b32_e32 v94, v0
	v_mov_b32_e32 v95, v0
	v_mov_b32_e32 v100, v0
	v_mov_b32_e32 v101, v0
	v_mov_b32_e32 v102, v0
	v_mov_b32_e32 v103, v0
	v_mov_b32_e32 v108, v0
	v_mov_b32_e32 v109, v0
	v_mov_b32_e32 v110, v0
	v_mov_b32_e32 v111, v0
	v_mov_b32_e32 v116, v0
	v_mov_b32_e32 v117, v0
	v_mov_b32_e32 v118, v0
	v_mov_b32_e32 v119, v0
	v_mov_b32_e32 v124, v0
	v_mov_b32_e32 v125, v0
	v_mov_b32_e32 v126, v0
	v_mov_b32_e32 v127, v0
	v_readlane_b32 s5, v253, 17
	v_readlane_b32 s8, v253, 20
	v_readlane_b32 s9, v253, 21
	v_readlane_b32 s10, v253, 22
	v_readlane_b32 s11, v253, 23
	v_readlane_b32 s12, v253, 24
	v_readlane_b32 s13, v253, 25
	v_readlane_b32 s14, v253, 26
	v_readlane_b32 s15, v253, 27
	v_readlane_b32 s16, v253, 28
	v_readlane_b32 s17, v253, 29
	v_readlane_b32 s18, v253, 30
	v_readlane_b32 s19, v253, 31
	v_add_u32_e32 v230, 0x10000, v140
.LBB0_66:
	ds_read_b128 v[142:145], v230
	ds_read_b128 v[146:149], v230 offset:1024
	ds_read_b128 v[150:153], v230 offset:2048
	ds_read_b128 v[154:157], v230 offset:3072
	s_add_u32 s42, s40, 0xfffc0080
	s_addc_u32 s43, s41, -1
	s_cmp_eq_u32 s96, 12
	s_cselect_b32 s45, s31, s43
	s_cselect_b32 s44, s80, s42
	s_cselect_b32 s43, s29, s27
	s_cselect_b32 s42, vcc_lo, s26
	s_mov_b32 m0, s69
	v_lshl_add_u64 v[182:183], s[40:41], 0, v[134:135]
	ds_read_b128 v[158:161], v139
	ds_read_b128 v[162:165], v139 offset:1024
	ds_read_b128 v[166:169], v139 offset:2048
	ds_read_b128 v[170:173], v139 offset:3072
	ds_read_b128 v[174:177], v139 offset:4096
	ds_read_b128 v[178:181], v139 offset:5120
	ds_read_b128 v[186:189], v139 offset:6144
	ds_read_b128 v[194:197], v139 offset:7168
	global_load_lds_dwordx4 v[182:183], off
	v_lshl_add_u64 v[182:183], s[40:41], 0, v[136:137]
	s_mov_b32 m0, s70
	s_nop 0
	global_load_lds_dwordx4 v[182:183], off
	ds_read_b128 v[198:201], v230 offset:16384
	ds_read_b128 v[202:205], v230 offset:17408
	ds_read_b128 v[206:209], v230 offset:18432
	ds_read_b128 v[210:213], v230 offset:19456
	s_waitcnt vmcnt(8) lgkmcnt(0)
	s_barrier
	v_mfma_f32_16x16x32_bf16 v[124:127], v[142:145], v[158:161], v[124:127]
	v_mfma_f32_16x16x32_bf16 v[116:119], v[150:153], v[158:161], v[116:119]
	v_mfma_f32_16x16x32_bf16 v[108:111], v[142:145], v[166:169], v[108:111]
	v_mfma_f32_16x16x32_bf16 v[100:103], v[150:153], v[166:169], v[100:103]
	v_mfma_f32_16x16x32_bf16 v[92:95], v[142:145], v[174:177], v[92:95]
	v_mfma_f32_16x16x32_bf16 v[84:87], v[150:153], v[174:177], v[84:87]
	v_mfma_f32_16x16x32_bf16 v[76:79], v[142:145], v[186:189], v[76:79]
	v_mfma_f32_16x16x32_bf16 v[68:71], v[150:153], v[186:189], v[68:71]
	v_mfma_f32_16x16x32_bf16 v[124:127], v[146:149], v[162:165], v[124:127]
	v_mfma_f32_16x16x32_bf16 v[116:119], v[154:157], v[162:165], v[116:119]
	v_mfma_f32_16x16x32_bf16 v[108:111], v[146:149], v[170:173], v[108:111]
	v_mfma_f32_16x16x32_bf16 v[100:103], v[154:157], v[170:173], v[100:103]
	v_mfma_f32_16x16x32_bf16 v[92:95], v[146:149], v[178:181], v[92:95]
	v_mfma_f32_16x16x32_bf16 v[84:87], v[154:157], v[178:181], v[84:87]
	v_mfma_f32_16x16x32_bf16 v[76:79], v[146:149], v[194:197], v[76:79]
	v_mfma_f32_16x16x32_bf16 v[68:71], v[154:157], v[194:197], v[68:71]
	v_mfma_f32_16x16x32_bf16 v[120:123], v[198:201], v[158:161], v[120:123]
	v_mfma_f32_16x16x32_bf16 v[112:115], v[206:209], v[158:161], v[112:115]
	v_mfma_f32_16x16x32_bf16 v[104:107], v[198:201], v[166:169], v[104:107]
	v_mfma_f32_16x16x32_bf16 v[96:99], v[206:209], v[166:169], v[96:99]
	v_mfma_f32_16x16x32_bf16 v[88:91], v[198:201], v[174:177], v[88:91]
	v_mfma_f32_16x16x32_bf16 v[80:83], v[206:209], v[174:177], v[80:83]
	v_mfma_f32_16x16x32_bf16 v[72:75], v[198:201], v[186:189], v[72:75]
	v_mfma_f32_16x16x32_bf16 v[64:67], v[206:209], v[186:189], v[64:67]
	v_mfma_f32_16x16x32_bf16 v[120:123], v[202:205], v[162:165], v[120:123]
	v_mfma_f32_16x16x32_bf16 v[112:115], v[210:213], v[162:165], v[112:115]
	v_mfma_f32_16x16x32_bf16 v[104:107], v[202:205], v[170:173], v[104:107]
	v_mfma_f32_16x16x32_bf16 v[96:99], v[210:213], v[170:173], v[96:99]
	v_mfma_f32_16x16x32_bf16 v[88:91], v[202:205], v[178:181], v[88:91]
	v_mfma_f32_16x16x32_bf16 v[80:83], v[210:213], v[178:181], v[80:83]
	v_mfma_f32_16x16x32_bf16 v[72:75], v[202:205], v[194:197], v[72:75]
	v_mfma_f32_16x16x32_bf16 v[64:67], v[210:213], v[194:197], v[64:67]
	s_barrier
	s_mov_b32 m0, s39
	v_lshl_add_u64 v[182:183], s[42:43], 0, v[184:185]
	global_load_lds_dwordx4 v[182:183], off
	v_lshl_add_u64 v[190:191], s[42:43], 0, v[128:129]
	s_mov_b32 m0, s53
	s_nop 0
	global_load_lds_dwordx4 v[190:191], off
	s_mov_b32 m0, s50
	v_lshl_add_u64 v[214:215], s[44:45], 0, v[132:133]
	ds_read_b128 v[158:161], v139 offset:16384
	ds_read_b128 v[162:165], v139 offset:17408
	ds_read_b128 v[166:169], v139 offset:18432
	ds_read_b128 v[170:173], v139 offset:19456
	ds_read_b128 v[174:177], v139 offset:20480
	ds_read_b128 v[178:181], v139 offset:21504
	ds_read_b128 v[186:189], v139 offset:22528
	ds_read_b128 v[194:197], v139 offset:23552
	global_load_lds_dwordx4 v[214:215], off
	v_lshl_add_u64 v[216:217], s[44:45], 0, v[130:131]
	s_mov_b32 m0, s54
	s_nop 0
	global_load_lds_dwordx4 v[216:217], off
	s_waitcnt vmcnt(6) lgkmcnt(0)
	s_barrier
	s_cmp_lg_u32 s100, 0
	s_cbranch_scc1 .Lmskip_66_2
	v_mfma_f32_16x16x32_bf16 v[60:63], v[142:145], v[158:161], v[60:63]
	v_mfma_f32_16x16x32_bf16 v[52:55], v[150:153], v[158:161], v[52:55]
	v_mfma_f32_16x16x32_bf16 v[44:47], v[142:145], v[166:169], v[44:47]
	v_mfma_f32_16x16x32_bf16 v[36:39], v[150:153], v[166:169], v[36:39]
	v_mfma_f32_16x16x32_bf16 v[28:31], v[142:145], v[174:177], v[28:31]
	v_mfma_f32_16x16x32_bf16 v[20:23], v[150:153], v[174:177], v[20:23]
	v_mfma_f32_16x16x32_bf16 v[12:15], v[142:145], v[186:189], v[12:15]
	v_mfma_f32_16x16x32_bf16 v[4:7], v[150:153], v[186:189], v[4:7]
	v_mfma_f32_16x16x32_bf16 v[60:63], v[146:149], v[162:165], v[60:63]
	v_mfma_f32_16x16x32_bf16 v[52:55], v[154:157], v[162:165], v[52:55]
	v_mfma_f32_16x16x32_bf16 v[44:47], v[146:149], v[170:173], v[44:47]
	v_mfma_f32_16x16x32_bf16 v[36:39], v[154:157], v[170:173], v[36:39]
	v_mfma_f32_16x16x32_bf16 v[28:31], v[146:149], v[178:181], v[28:31]
	v_mfma_f32_16x16x32_bf16 v[20:23], v[154:157], v[178:181], v[20:23]
	v_mfma_f32_16x16x32_bf16 v[12:15], v[146:149], v[194:197], v[12:15]
	v_mfma_f32_16x16x32_bf16 v[4:7], v[154:157], v[194:197], v[4:7]
	v_mfma_f32_16x16x32_bf16 v[56:59], v[198:201], v[158:161], v[56:59]
	v_mfma_f32_16x16x32_bf16 v[48:51], v[206:209], v[158:161], v[48:51]
	v_mfma_f32_16x16x32_bf16 v[40:43], v[198:201], v[166:169], v[40:43]
	v_mfma_f32_16x16x32_bf16 v[32:35], v[206:209], v[166:169], v[32:35]
	v_mfma_f32_16x16x32_bf16 v[24:27], v[198:201], v[174:177], v[24:27]
	v_mfma_f32_16x16x32_bf16 v[16:19], v[206:209], v[174:177], v[16:19]
	v_mfma_f32_16x16x32_bf16 v[8:11], v[198:201], v[186:189], v[8:11]
	v_mfma_f32_16x16x32_bf16 v[0:3], v[206:209], v[186:189], v[0:3]
	v_mfma_f32_16x16x32_bf16 v[56:59], v[202:205], v[162:165], v[56:59]
	v_mfma_f32_16x16x32_bf16 v[48:51], v[210:213], v[162:165], v[48:51]
	v_mfma_f32_16x16x32_bf16 v[40:43], v[202:205], v[170:173], v[40:43]
	v_mfma_f32_16x16x32_bf16 v[32:35], v[210:213], v[170:173], v[32:35]
	v_mfma_f32_16x16x32_bf16 v[24:27], v[202:205], v[178:181], v[24:27]
	v_mfma_f32_16x16x32_bf16 v[16:19], v[210:213], v[178:181], v[16:19]
	v_mfma_f32_16x16x32_bf16 v[8:11], v[202:205], v[194:197], v[8:11]
	v_mfma_f32_16x16x32_bf16 v[0:3], v[210:213], v[194:197], v[0:3]
.Lmskip_66_2:
	s_barrier
	s_add_u32 s66, s42, 0x40000
	s_addc_u32 s67, s43, 0
	s_mov_b32 m0, s55
	v_lshl_add_u64 v[142:143], s[66:67], 0, v[184:185]
	global_load_lds_dwordx4 v[142:143], off
	v_lshl_add_u64 v[142:143], s[66:67], 0, v[128:129]
	s_mov_b32 m0, s58
	s_nop 0
	global_load_lds_dwordx4 v[142:143], off
	ds_read_b128 v[142:145], v230 offset:32768
	ds_read_b128 v[146:149], v230 offset:33792
	ds_read_b128 v[150:153], v230 offset:34816
	ds_read_b128 v[154:157], v230 offset:35840
	s_add_u32 s44, s44, 0x40000
	s_addc_u32 s45, s45, 0
	s_mov_b32 m0, s59
	v_lshl_add_u64 v[198:199], s[44:45], 0, v[132:133]
	ds_read_b128 v[158:161], v139 offset:32768
	ds_read_b128 v[162:165], v139 offset:33792
	ds_read_b128 v[166:169], v139 offset:34816
	ds_read_b128 v[170:173], v139 offset:35840
	ds_read_b128 v[174:177], v139 offset:36864
	ds_read_b128 v[178:181], v139 offset:37888
	ds_read_b128 v[186:189], v139 offset:38912
	ds_read_b128 v[194:197], v139 offset:39936
	global_load_lds_dwordx4 v[198:199], off
	v_lshl_add_u64 v[198:199], s[44:45], 0, v[130:131]
	s_mov_b32 m0, s60
	s_nop 0
	global_load_lds_dwordx4 v[198:199], off
	ds_read_b128 v[198:201], v230 offset:49152
	ds_read_b128 v[202:205], v230 offset:50176
	ds_read_b128 v[206:209], v230 offset:51200
	ds_read_b128 v[210:213], v230 offset:52224
	s_waitcnt vmcnt(8) lgkmcnt(0)
	s_barrier
	v_mfma_f32_16x16x32_bf16 v[124:127], v[142:145], v[158:161], v[124:127]
	v_mfma_f32_16x16x32_bf16 v[116:119], v[150:153], v[158:161], v[116:119]
	v_mfma_f32_16x16x32_bf16 v[108:111], v[142:145], v[166:169], v[108:111]
	v_mfma_f32_16x16x32_bf16 v[100:103], v[150:153], v[166:169], v[100:103]
	v_mfma_f32_16x16x32_bf16 v[92:95], v[142:145], v[174:177], v[92:95]
	v_mfma_f32_16x16x32_bf16 v[84:87], v[150:153], v[174:177], v[84:87]
	v_mfma_f32_16x16x32_bf16 v[76:79], v[142:145], v[186:189], v[76:79]
	v_mfma_f32_16x16x32_bf16 v[68:71], v[150:153], v[186:189], v[68:71]
	v_mfma_f32_16x16x32_bf16 v[124:127], v[146:149], v[162:165], v[124:127]
	v_mfma_f32_16x16x32_bf16 v[116:119], v[154:157], v[162:165], v[116:119]
	v_mfma_f32_16x16x32_bf16 v[108:111], v[146:149], v[170:173], v[108:111]
	v_mfma_f32_16x16x32_bf16 v[100:103], v[154:157], v[170:173], v[100:103]
	v_mfma_f32_16x16x32_bf16 v[92:95], v[146:149], v[178:181], v[92:95]
	v_mfma_f32_16x16x32_bf16 v[84:87], v[154:157], v[178:181], v[84:87]
	v_mfma_f32_16x16x32_bf16 v[76:79], v[146:149], v[194:197], v[76:79]
	v_mfma_f32_16x16x32_bf16 v[68:71], v[154:157], v[194:197], v[68:71]
	v_mfma_f32_16x16x32_bf16 v[120:123], v[198:201], v[158:161], v[120:123]
	v_mfma_f32_16x16x32_bf16 v[112:115], v[206:209], v[158:161], v[112:115]
	v_mfma_f32_16x16x32_bf16 v[104:107], v[198:201], v[166:169], v[104:107]
	v_mfma_f32_16x16x32_bf16 v[96:99], v[206:209], v[166:169], v[96:99]
	v_mfma_f32_16x16x32_bf16 v[88:91], v[198:201], v[174:177], v[88:91]
	v_mfma_f32_16x16x32_bf16 v[80:83], v[206:209], v[174:177], v[80:83]
	v_mfma_f32_16x16x32_bf16 v[72:75], v[198:201], v[186:189], v[72:75]
	v_mfma_f32_16x16x32_bf16 v[64:67], v[206:209], v[186:189], v[64:67]
	v_mfma_f32_16x16x32_bf16 v[120:123], v[202:205], v[162:165], v[120:123]
	v_mfma_f32_16x16x32_bf16 v[112:115], v[210:213], v[162:165], v[112:115]
	v_mfma_f32_16x16x32_bf16 v[104:107], v[202:205], v[170:173], v[104:107]
	v_mfma_f32_16x16x32_bf16 v[96:99], v[210:213], v[170:173], v[96:99]
	v_mfma_f32_16x16x32_bf16 v[88:91], v[202:205], v[178:181], v[88:91]
	v_mfma_f32_16x16x32_bf16 v[80:83], v[210:213], v[178:181], v[80:83]
	v_mfma_f32_16x16x32_bf16 v[72:75], v[202:205], v[194:197], v[72:75]
	v_mfma_f32_16x16x32_bf16 v[64:67], v[210:213], v[194:197], v[64:67]
	s_barrier
	s_mov_b32 m0, s33
	v_lshl_add_u64 v[182:183], v[182:183], 0, s[24:25]
	global_load_lds_dwordx4 v[182:183], off
	v_lshl_add_u64 v[182:183], v[190:191], 0, s[24:25]
	s_mov_b32 m0, s61
	s_nop 0
	global_load_lds_dwordx4 v[182:183], off
	s_mov_b32 m0, s62
	v_lshl_add_u64 v[182:183], v[214:215], 0, s[24:25]
	ds_read_b128 v[158:161], v139 offset:49152
	ds_read_b128 v[162:165], v139 offset:50176
	ds_read_b128 v[166:169], v139 offset:51200
	ds_read_b128 v[170:173], v139 offset:52224
	ds_read_b128 v[174:177], v139 offset:53248
	ds_read_b128 v[178:181], v139 offset:54272
	ds_read_b128 v[186:189], v139 offset:55296
	ds_read_b128 v[194:197], v139 offset:56320
	global_load_lds_dwordx4 v[182:183], off
	v_lshl_add_u64 v[182:183], v[216:217], 0, s[24:25]
	s_mov_b32 m0, s63
	s_nop 0
	global_load_lds_dwordx4 v[182:183], off
	s_waitcnt vmcnt(6) lgkmcnt(0)
	s_barrier
	s_cmp_lg_u32 s100, 0
	s_cbranch_scc1 .Lmskip_66_6
	v_mfma_f32_16x16x32_bf16 v[60:63], v[142:145], v[158:161], v[60:63]
	v_mfma_f32_16x16x32_bf16 v[52:55], v[150:153], v[158:161], v[52:55]
	v_mfma_f32_16x16x32_bf16 v[44:47], v[142:145], v[166:169], v[44:47]
	v_mfma_f32_16x16x32_bf16 v[36:39], v[150:153], v[166:169], v[36:39]
	v_mfma_f32_16x16x32_bf16 v[28:31], v[142:145], v[174:177], v[28:31]
	v_mfma_f32_16x16x32_bf16 v[20:23], v[150:153], v[174:177], v[20:23]
	v_mfma_f32_16x16x32_bf16 v[12:15], v[142:145], v[186:189], v[12:15]
	v_mfma_f32_16x16x32_bf16 v[4:7], v[150:153], v[186:189], v[4:7]
	v_mfma_f32_16x16x32_bf16 v[60:63], v[146:149], v[162:165], v[60:63]
	v_mfma_f32_16x16x32_bf16 v[52:55], v[154:157], v[162:165], v[52:55]
	v_mfma_f32_16x16x32_bf16 v[44:47], v[146:149], v[170:173], v[44:47]
	v_mfma_f32_16x16x32_bf16 v[36:39], v[154:157], v[170:173], v[36:39]
	v_mfma_f32_16x16x32_bf16 v[28:31], v[146:149], v[178:181], v[28:31]
	v_mfma_f32_16x16x32_bf16 v[20:23], v[154:157], v[178:181], v[20:23]
	v_mfma_f32_16x16x32_bf16 v[12:15], v[146:149], v[194:197], v[12:15]
	v_mfma_f32_16x16x32_bf16 v[4:7], v[154:157], v[194:197], v[4:7]
	v_mfma_f32_16x16x32_bf16 v[56:59], v[198:201], v[158:161], v[56:59]
	v_mfma_f32_16x16x32_bf16 v[48:51], v[206:209], v[158:161], v[48:51]
	v_mfma_f32_16x16x32_bf16 v[40:43], v[198:201], v[166:169], v[40:43]
	v_mfma_f32_16x16x32_bf16 v[32:35], v[206:209], v[166:169], v[32:35]
	v_mfma_f32_16x16x32_bf16 v[24:27], v[198:201], v[174:177], v[24:27]
	v_mfma_f32_16x16x32_bf16 v[16:19], v[206:209], v[174:177], v[16:19]
	v_mfma_f32_16x16x32_bf16 v[8:11], v[198:201], v[186:189], v[8:11]
	v_mfma_f32_16x16x32_bf16 v[0:3], v[206:209], v[186:189], v[0:3]
	v_mfma_f32_16x16x32_bf16 v[56:59], v[202:205], v[162:165], v[56:59]
	v_mfma_f32_16x16x32_bf16 v[48:51], v[210:213], v[162:165], v[48:51]
	v_mfma_f32_16x16x32_bf16 v[40:43], v[202:205], v[170:173], v[40:43]
	v_mfma_f32_16x16x32_bf16 v[32:35], v[210:213], v[170:173], v[32:35]
	v_mfma_f32_16x16x32_bf16 v[24:27], v[202:205], v[178:181], v[24:27]
	v_mfma_f32_16x16x32_bf16 v[16:19], v[210:213], v[178:181], v[16:19]
	v_mfma_f32_16x16x32_bf16 v[8:11], v[202:205], v[194:197], v[8:11]
	v_mfma_f32_16x16x32_bf16 v[0:3], v[210:213], v[194:197], v[0:3]

.LBB0_86:
	v_lshrrev_b32_e32 v20, 1, v6
	v_and_b32_e32 v20, 24, v20
	v_and_b32_e32 v7, 15, v6
	v_lshlrev_b32_e32 v21, 1, v20
	v_lshlrev_b32_e32 v6, 2, v6
	s_sext_i32_i8 s70, s0
	v_lshl_or_b32 v140, s27, 6, v7
	v_lshl_or_b32 v7, v7, 6, v21
	s_lshl_b32 s0, s27, 13
	v_and_b32_e32 v6, 32, v6
	v_bitop3_b32 v141, v7, s0, v6 bitop3:0xde
	s_lshl_b32 s0, s1, 5
	s_and_b32 s0, s0, 0x60
	v_lshl_add_u64 v[8:9], s[34:35], 0, v[184:185]
	v_mov_b32_e32 v129, v185
	s_lshl_b32 s1, s0, 7
	s_add_i32 s55, s44, 0x18000
	v_lshl_add_u64 v[10:11], s[34:35], 0, v[128:129]
	v_mov_b32_e32 v133, v185
	v_bitop3_b32 v142, v7, s1, v6 bitop3:0xde
	v_lshl_add_u64 v[6:7], v[8:9], 0, s[24:25]
	s_mov_b32 m0, s55
	s_add_i32 s58, s44, 0x1a000
	v_lshl_add_u64 v[12:13], s[30:31], 0, v[132:133]
	v_mov_b32_e32 v131, v185
	s_waitcnt vmcnt(2)
	s_barrier
	global_load_lds_dwordx4 v[6:7], off
	v_lshl_add_u64 v[6:7], v[10:11], 0, s[24:25]
	s_mov_b32 m0, s58
	s_add_i32 s59, s44, 0x8000
	v_lshl_add_u64 v[14:15], s[30:31], 0, v[130:131]
	global_load_lds_dwordx4 v[6:7], off
	v_lshl_add_u64 v[6:7], v[12:13], 0, s[24:25]
	s_mov_b32 m0, s59
	s_add_i32 s60, s44, 0xa000
	v_lshl_add_u64 v[16:17], s[22:23], 0, v[184:185]
	global_load_lds_dwordx4 v[6:7], off
	v_lshl_add_u64 v[6:7], v[14:15], 0, s[24:25]
	s_mov_b32 m0, s60
	s_add_i32 s61, s44, 0x1c000
	v_lshl_add_u64 v[18:19], s[22:23], 0, v[128:129]
	global_load_lds_dwordx4 v[6:7], off
	v_lshl_add_u64 v[6:7], v[16:17], 0, s[24:25]
	s_mov_b32 m0, s61
	s_add_i32 s62, s44, 0x1e000
	global_load_lds_dwordx4 v[6:7], off
	v_lshl_add_u64 v[6:7], v[18:19], 0, s[24:25]
	s_mov_b32 m0, s62
	v_add_u32_e32 v3, v5, v3
	global_load_lds_dwordx4 v[6:7], off
	s_waitcnt vmcnt(6)
	v_add_u32_e32 v0, v2, v0
	s_lshr_b32 s54, s26, 6
	v_add_lshl_u32 v4, v3, v4, 1
	v_mov_b32_e32 v5, v185
	v_add_lshl_u32 v0, v0, v1, 1
	v_mov_b32_e32 v1, v185
	s_add_i32 s63, s54, -2
	v_or_b32_e32 v143, s0, v20
	v_lshl_add_u64 v[134:135], s[88:89], 0, v[4:5]
	v_lshl_add_u64 v[136:137], s[88:89], 0, v[0:1]
	s_mov_b32 s64, 0
	s_barrier

.LBB0_93:
	s_add_u32 s30, s30, 0x80
	s_addc_u32 s31, s31, 0
	s_add_u32 s26, s34, 0x100
	v_mov_b32_e32 v0, 0
	s_addc_u32 s27, s35, 0
	s_mov_b32 s34, 0
	v_mov_b32_e32 v1, v0
	v_mov_b32_e32 v2, v0
	v_mov_b32_e32 v3, v0
	v_mov_b32_e32 v4, v0
	v_mov_b32_e32 v5, v0
	v_mov_b32_e32 v6, v0
	v_mov_b32_e32 v7, v0
	v_mov_b32_e32 v8, v0
	v_mov_b32_e32 v9, v0
	v_mov_b32_e32 v10, v0
	v_mov_b32_e32 v11, v0
	v_mov_b32_e32 v12, v0
	v_mov_b32_e32 v13, v0
	v_mov_b32_e32 v14, v0
	v_mov_b32_e32 v15, v0
	v_mov_b32_e32 v16, v0
	v_mov_b32_e32 v17, v0
	v_mov_b32_e32 v18, v0
	v_mov_b32_e32 v19, v0
	v_mov_b32_e32 v20, v0
	v_mov_b32_e32 v21, v0
	v_mov_b32_e32 v22, v0
	v_mov_b32_e32 v23, v0
	v_mov_b32_e32 v24, v0
	v_mov_b32_e32 v25, v0
	v_mov_b32_e32 v26, v0
	v_mov_b32_e32 v27, v0
	v_mov_b32_e32 v28, v0
	v_mov_b32_e32 v29, v0
	v_mov_b32_e32 v30, v0
	v_mov_b32_e32 v31, v0
	v_mov_b32_e32 v32, v0
	v_mov_b32_e32 v33, v0
	v_mov_b32_e32 v34, v0
	v_mov_b32_e32 v35, v0
	v_mov_b32_e32 v36, v0
	v_mov_b32_e32 v37, v0
	v_mov_b32_e32 v38, v0
	v_mov_b32_e32 v39, v0
	v_mov_b32_e32 v40, v0
	v_mov_b32_e32 v41, v0
	v_mov_b32_e32 v42, v0
	v_mov_b32_e32 v43, v0
	v_mov_b32_e32 v44, v0
	v_mov_b32_e32 v45, v0
	v_mov_b32_e32 v46, v0
	v_mov_b32_e32 v47, v0
	v_mov_b32_e32 v48, v0
	v_mov_b32_e32 v49, v0
	v_mov_b32_e32 v50, v0
	v_mov_b32_e32 v51, v0
	v_mov_b32_e32 v52, v0
	v_mov_b32_e32 v53, v0
	v_mov_b32_e32 v54, v0
	v_mov_b32_e32 v55, v0
	v_mov_b32_e32 v56, v0
	v_mov_b32_e32 v57, v0
	v_mov_b32_e32 v58, v0
	v_mov_b32_e32 v59, v0
	v_mov_b32_e32 v60, v0
	v_mov_b32_e32 v61, v0
	v_mov_b32_e32 v62, v0
	v_mov_b32_e32 v63, v0
	v_mov_b32_e32 v64, v0
	v_mov_b32_e32 v65, v0
	v_mov_b32_e32 v66, v0
	v_mov_b32_e32 v67, v0
	v_mov_b32_e32 v68, v0
	v_mov_b32_e32 v69, v0
	v_mov_b32_e32 v70, v0
	v_mov_b32_e32 v71, v0
	v_mov_b32_e32 v72, v0
	v_mov_b32_e32 v73, v0
	v_mov_b32_e32 v74, v0
	v_mov_b32_e32 v75, v0
	v_mov_b32_e32 v76, v0
	v_mov_b32_e32 v77, v0
	v_mov_b32_e32 v78, v0
	v_mov_b32_e32 v79, v0
	v_mov_b32_e32 v80, v0
	v_mov_b32_e32 v81, v0
	v_mov_b32_e32 v82, v0
	v_mov_b32_e32 v83, v0
	v_mov_b32_e32 v84, v0
	v_mov_b32_e32 v85, v0
	v_mov_b32_e32 v86, v0
	v_mov_b32_e32 v87, v0
	v_mov_b32_e32 v88, v0
	v_mov_b32_e32 v89, v0
	v_mov_b32_e32 v90, v0
	v_mov_b32_e32 v91, v0
	v_mov_b32_e32 v92, v0
	v_mov_b32_e32 v93, v0
	v_mov_b32_e32 v94, v0
	v_mov_b32_e32 v95, v0
	v_mov_b32_e32 v96, v0
	v_mov_b32_e32 v97, v0
	v_mov_b32_e32 v98, v0
	v_mov_b32_e32 v99, v0
	v_mov_b32_e32 v100, v0
	v_mov_b32_e32 v101, v0
	v_mov_b32_e32 v102, v0
	v_mov_b32_e32 v103, v0
	v_mov_b32_e32 v104, v0
	v_mov_b32_e32 v105, v0
	v_mov_b32_e32 v106, v0
	v_mov_b32_e32 v107, v0
	v_mov_b32_e32 v108, v0
	v_mov_b32_e32 v109, v0
	v_mov_b32_e32 v110, v0
	v_mov_b32_e32 v111, v0
	v_mov_b32_e32 v112, v0
	v_mov_b32_e32 v113, v0
	v_mov_b32_e32 v114, v0
	v_mov_b32_e32 v115, v0
	v_mov_b32_e32 v116, v0
	v_mov_b32_e32 v117, v0
	v_mov_b32_e32 v118, v0
	v_mov_b32_e32 v119, v0
	v_mov_b32_e32 v120, v0
	v_mov_b32_e32 v121, v0
	v_mov_b32_e32 v122, v0
	v_mov_b32_e32 v123, v0
	v_mov_b32_e32 v124, v0
	v_mov_b32_e32 v125, v0
	v_mov_b32_e32 v126, v0
	v_mov_b32_e32 v127, v0
	s_cmp_lg_u32 s100, 0
	s_cselect_b64 vcc, -1, 0
	v_add_u32_e32 v251, 0x10000, v142
.LBB0_94:
	ds_read_b128 v[144:147], v251
	ds_read_b128 v[148:151], v251 offset:1024
	s_add_i32 s71, s34, 2
	ds_read_b128 v[152:155], v251 offset:2048
	ds_read_b128 v[156:159], v251 offset:3072
	s_add_u32 s36, s30, 0x80
	s_addc_u32 s35, s31, 0
	s_cmp_eq_u32 s63, s34
	s_cselect_b32 s34, s28, s36
	s_cselect_b32 s35, s29, s35
	s_cselect_b32 s37, s1, s27
	s_cselect_b32 s36, s0, s26
	v_lshl_add_u64 v[138:139], s[30:31], 0, v[134:135]
	s_add_i32 m0, s44, 0xc000
	ds_read_b128 v[160:163], v141
	ds_read_b128 v[164:167], v141 offset:1024
	ds_read_b128 v[168:171], v141 offset:2048
	ds_read_b128 v[172:175], v141 offset:3072
	ds_read_b128 v[176:179], v141 offset:4096
	ds_read_b128 v[180:183], v141 offset:5120
	ds_read_b128 v[186:189], v141 offset:6144
	ds_read_b128 v[194:197], v141 offset:7168
	global_load_lds_dwordx4 v[138:139], off
	v_lshl_add_u64 v[138:139], s[30:31], 0, v[136:137]
	s_add_i32 m0, s44, 0xe000
	s_nop 0
	global_load_lds_dwordx4 v[138:139], off
	ds_read_b128 v[198:201], v251 offset:16384
	ds_read_b128 v[202:205], v251 offset:17408
	ds_read_b128 v[206:209], v251 offset:18432
	ds_read_b128 v[210:213], v251 offset:19456
	s_waitcnt vmcnt(8) lgkmcnt(0)
	s_barrier
	v_mfma_f32_16x16x32_bf16 v[124:127], v[144:147], v[160:163], v[124:127]
	v_mfma_f32_16x16x32_bf16 v[120:123], v[152:155], v[160:163], v[120:123]
	v_mfma_f32_16x16x32_bf16 v[116:119], v[144:147], v[168:171], v[116:119]
	v_mfma_f32_16x16x32_bf16 v[112:115], v[152:155], v[168:171], v[112:115]
	v_mfma_f32_16x16x32_bf16 v[108:111], v[144:147], v[176:179], v[108:111]
	v_mfma_f32_16x16x32_bf16 v[104:107], v[152:155], v[176:179], v[104:107]
	v_mfma_f32_16x16x32_bf16 v[100:103], v[144:147], v[186:189], v[100:103]
	v_mfma_f32_16x16x32_bf16 v[96:99], v[152:155], v[186:189], v[96:99]
	v_mfma_f32_16x16x32_bf16 v[124:127], v[148:151], v[164:167], v[124:127]
	v_mfma_f32_16x16x32_bf16 v[120:123], v[156:159], v[164:167], v[120:123]
	v_mfma_f32_16x16x32_bf16 v[116:119], v[148:151], v[172:175], v[116:119]
	v_mfma_f32_16x16x32_bf16 v[112:115], v[156:159], v[172:175], v[112:115]
	v_mfma_f32_16x16x32_bf16 v[108:111], v[148:151], v[180:183], v[108:111]
	v_mfma_f32_16x16x32_bf16 v[104:107], v[156:159], v[180:183], v[104:107]
	v_mfma_f32_16x16x32_bf16 v[100:103], v[148:151], v[194:197], v[100:103]
	v_mfma_f32_16x16x32_bf16 v[96:99], v[156:159], v[194:197], v[96:99]
	v_mfma_f32_16x16x32_bf16 v[92:95], v[198:201], v[160:163], v[92:95]
	v_mfma_f32_16x16x32_bf16 v[88:91], v[206:209], v[160:163], v[88:91]
	v_mfma_f32_16x16x32_bf16 v[84:87], v[198:201], v[168:171], v[84:87]
	v_mfma_f32_16x16x32_bf16 v[80:83], v[206:209], v[168:171], v[80:83]
	v_mfma_f32_16x16x32_bf16 v[76:79], v[198:201], v[176:179], v[76:79]
	v_mfma_f32_16x16x32_bf16 v[72:75], v[206:209], v[176:179], v[72:75]
	v_mfma_f32_16x16x32_bf16 v[68:71], v[198:201], v[186:189], v[68:71]
	v_mfma_f32_16x16x32_bf16 v[64:67], v[206:209], v[186:189], v[64:67]
	v_mfma_f32_16x16x32_bf16 v[92:95], v[202:205], v[164:167], v[92:95]
	v_mfma_f32_16x16x32_bf16 v[88:91], v[210:213], v[164:167], v[88:91]
	v_mfma_f32_16x16x32_bf16 v[84:87], v[202:205], v[172:175], v[84:87]
	v_mfma_f32_16x16x32_bf16 v[80:83], v[210:213], v[172:175], v[80:83]
	v_mfma_f32_16x16x32_bf16 v[76:79], v[202:205], v[180:183], v[76:79]
	v_mfma_f32_16x16x32_bf16 v[72:75], v[210:213], v[180:183], v[72:75]
	v_mfma_f32_16x16x32_bf16 v[68:71], v[202:205], v[194:197], v[68:71]
	v_mfma_f32_16x16x32_bf16 v[64:67], v[210:213], v[194:197], v[64:67]
	s_barrier
	s_mov_b32 m0, s47
	v_lshl_add_u64 v[138:139], s[36:37], 0, v[184:185]
	global_load_lds_dwordx4 v[138:139], off
	v_lshl_add_u64 v[190:191], s[36:37], 0, v[128:129]
	s_mov_b32 m0, s48
	s_nop 0
	global_load_lds_dwordx4 v[190:191], off
	s_mov_b32 m0, s44
	v_lshl_add_u64 v[214:215], s[34:35], 0, v[132:133]
	ds_read_b128 v[160:163], v141 offset:16384
	ds_read_b128 v[164:167], v141 offset:17408
	ds_read_b128 v[168:171], v141 offset:18432
	ds_read_b128 v[172:175], v141 offset:19456
	ds_read_b128 v[176:179], v141 offset:20480
	ds_read_b128 v[180:183], v141 offset:21504
	ds_read_b128 v[186:189], v141 offset:22528
	ds_read_b128 v[194:197], v141 offset:23552
	global_load_lds_dwordx4 v[214:215], off
	v_lshl_add_u64 v[216:217], s[34:35], 0, v[130:131]
	s_mov_b32 m0, s49
	s_nop 0
	global_load_lds_dwordx4 v[216:217], off
	s_waitcnt vmcnt(6) lgkmcnt(0)
	s_barrier
	s_cbranch_vccnz .Lmskip_94_2
	v_mfma_f32_16x16x32_bf16 v[60:63], v[144:147], v[160:163], v[60:63]
	v_mfma_f32_16x16x32_bf16 v[56:59], v[152:155], v[160:163], v[56:59]
	v_mfma_f32_16x16x32_bf16 v[52:55], v[144:147], v[168:171], v[52:55]
	v_mfma_f32_16x16x32_bf16 v[48:51], v[152:155], v[168:171], v[48:51]
	v_mfma_f32_16x16x32_bf16 v[44:47], v[144:147], v[176:179], v[44:47]
	v_mfma_f32_16x16x32_bf16 v[40:43], v[152:155], v[176:179], v[40:43]
	v_mfma_f32_16x16x32_bf16 v[36:39], v[144:147], v[186:189], v[36:39]
	v_mfma_f32_16x16x32_bf16 v[32:35], v[152:155], v[186:189], v[32:35]
	v_mfma_f32_16x16x32_bf16 v[60:63], v[148:151], v[164:167], v[60:63]
	v_mfma_f32_16x16x32_bf16 v[56:59], v[156:159], v[164:167], v[56:59]
	v_mfma_f32_16x16x32_bf16 v[52:55], v[148:151], v[172:175], v[52:55]
	v_mfma_f32_16x16x32_bf16 v[48:51], v[156:159], v[172:175], v[48:51]
	v_mfma_f32_16x16x32_bf16 v[44:47], v[148:151], v[180:183], v[44:47]
	v_mfma_f32_16x16x32_bf16 v[40:43], v[156:159], v[180:183], v[40:43]
	v_mfma_f32_16x16x32_bf16 v[36:39], v[148:151], v[194:197], v[36:39]
	v_mfma_f32_16x16x32_bf16 v[32:35], v[156:159], v[194:197], v[32:35]
	v_mfma_f32_16x16x32_bf16 v[28:31], v[198:201], v[160:163], v[28:31]
	v_mfma_f32_16x16x32_bf16 v[24:27], v[206:209], v[160:163], v[24:27]
	v_mfma_f32_16x16x32_bf16 v[20:23], v[198:201], v[168:171], v[20:23]
	v_mfma_f32_16x16x32_bf16 v[16:19], v[206:209], v[168:171], v[16:19]
	v_mfma_f32_16x16x32_bf16 v[12:15], v[198:201], v[176:179], v[12:15]
	v_mfma_f32_16x16x32_bf16 v[8:11], v[206:209], v[176:179], v[8:11]
	v_mfma_f32_16x16x32_bf16 v[4:7], v[198:201], v[186:189], v[4:7]
	v_mfma_f32_16x16x32_bf16 v[0:3], v[206:209], v[186:189], v[0:3]
	v_mfma_f32_16x16x32_bf16 v[28:31], v[202:205], v[164:167], v[28:31]
	v_mfma_f32_16x16x32_bf16 v[24:27], v[210:213], v[164:167], v[24:27]
	v_mfma_f32_16x16x32_bf16 v[20:23], v[202:205], v[172:175], v[20:23]
	v_mfma_f32_16x16x32_bf16 v[16:19], v[210:213], v[172:175], v[16:19]
	v_mfma_f32_16x16x32_bf16 v[12:15], v[202:205], v[180:183], v[12:15]
	v_mfma_f32_16x16x32_bf16 v[8:11], v[210:213], v[180:183], v[8:11]
	v_mfma_f32_16x16x32_bf16 v[4:7], v[202:205], v[194:197], v[4:7]
	v_mfma_f32_16x16x32_bf16 v[0:3], v[210:213], v[194:197], v[0:3]
.Lmskip_94_2:
	s_barrier
	s_add_u32 s36, s36, s88
	s_addc_u32 s37, s37, 0
	s_mov_b32 m0, s50
	v_lshl_add_u64 v[230:231], s[36:37], 0, v[184:185]
	global_load_lds_dwordx4 v[230:231], off
	v_lshl_add_u64 v[232:233], s[36:37], 0, v[128:129]
	s_mov_b32 m0, s51
	s_nop 0
	global_load_lds_dwordx4 v[232:233], off
	ds_read_b128 v[144:147], v251 offset:32768
	ds_read_b128 v[148:151], v251 offset:33792
	ds_read_b128 v[152:155], v251 offset:34816
	ds_read_b128 v[156:159], v251 offset:35840
	s_add_u32 s34, s34, s88
	s_addc_u32 s35, s35, 0
	s_mov_b32 m0, s52
	v_lshl_add_u64 v[198:199], s[34:35], 0, v[132:133]
	ds_read_b128 v[160:163], v141 offset:32768
	ds_read_b128 v[164:167], v141 offset:33792
	ds_read_b128 v[168:171], v141 offset:34816
	ds_read_b128 v[172:175], v141 offset:35840
	ds_read_b128 v[176:179], v141 offset:36864
	ds_read_b128 v[180:183], v141 offset:37888
	ds_read_b128 v[186:189], v141 offset:38912
	ds_read_b128 v[194:197], v141 offset:39936
	global_load_lds_dwordx4 v[198:199], off
	v_lshl_add_u64 v[198:199], s[34:35], 0, v[130:131]
	s_mov_b32 m0, s53
	s_nop 0
	global_load_lds_dwordx4 v[198:199], off
	ds_read_b128 v[198:201], v251 offset:49152
	ds_read_b128 v[202:205], v251 offset:50176
	ds_read_b128 v[206:209], v251 offset:51200
	ds_read_b128 v[210:213], v251 offset:52224
	s_waitcnt vmcnt(8) lgkmcnt(0)
	s_barrier
	v_mfma_f32_16x16x32_bf16 v[124:127], v[144:147], v[160:163], v[124:127]
	v_mfma_f32_16x16x32_bf16 v[120:123], v[152:155], v[160:163], v[120:123]
	v_mfma_f32_16x16x32_bf16 v[116:119], v[144:147], v[168:171], v[116:119]
	v_mfma_f32_16x16x32_bf16 v[112:115], v[152:155], v[168:171], v[112:115]
	v_mfma_f32_16x16x32_bf16 v[108:111], v[144:147], v[176:179], v[108:111]
	v_mfma_f32_16x16x32_bf16 v[104:107], v[152:155], v[176:179], v[104:107]
	v_mfma_f32_16x16x32_bf16 v[100:103], v[144:147], v[186:189], v[100:103]
	v_mfma_f32_16x16x32_bf16 v[96:99], v[152:155], v[186:189], v[96:99]
	v_mfma_f32_16x16x32_bf16 v[124:127], v[148:151], v[164:167], v[124:127]
	v_mfma_f32_16x16x32_bf16 v[120:123], v[156:159], v[164:167], v[120:123]
	v_mfma_f32_16x16x32_bf16 v[116:119], v[148:151], v[172:175], v[116:119]
	v_mfma_f32_16x16x32_bf16 v[112:115], v[156:159], v[172:175], v[112:115]
	v_mfma_f32_16x16x32_bf16 v[108:111], v[148:151], v[180:183], v[108:111]
	v_mfma_f32_16x16x32_bf16 v[104:107], v[156:159], v[180:183], v[104:107]
	v_mfma_f32_16x16x32_bf16 v[100:103], v[148:151], v[194:197], v[100:103]
	v_mfma_f32_16x16x32_bf16 v[96:99], v[156:159], v[194:197], v[96:99]
	v_mfma_f32_16x16x32_bf16 v[92:95], v[198:201], v[160:163], v[92:95]
	v_mfma_f32_16x16x32_bf16 v[88:91], v[206:209], v[160:163], v[88:91]
	v_mfma_f32_16x16x32_bf16 v[84:87], v[198:201], v[168:171], v[84:87]
	v_mfma_f32_16x16x32_bf16 v[80:83], v[206:209], v[168:171], v[80:83]
	v_mfma_f32_16x16x32_bf16 v[76:79], v[198:201], v[176:179], v[76:79]
	v_mfma_f32_16x16x32_bf16 v[72:75], v[206:209], v[176:179], v[72:75]
	v_mfma_f32_16x16x32_bf16 v[68:71], v[198:201], v[186:189], v[68:71]
	v_mfma_f32_16x16x32_bf16 v[64:67], v[206:209], v[186:189], v[64:67]
	v_mfma_f32_16x16x32_bf16 v[92:95], v[202:205], v[164:167], v[92:95]
	v_mfma_f32_16x16x32_bf16 v[88:91], v[210:213], v[164:167], v[88:91]
	v_mfma_f32_16x16x32_bf16 v[84:87], v[202:205], v[172:175], v[84:87]
	v_mfma_f32_16x16x32_bf16 v[80:83], v[210:213], v[172:175], v[80:83]
	v_mfma_f32_16x16x32_bf16 v[76:79], v[202:205], v[180:183], v[76:79]
	v_mfma_f32_16x16x32_bf16 v[72:75], v[210:213], v[180:183], v[72:75]
	v_mfma_f32_16x16x32_bf16 v[68:71], v[202:205], v[194:197], v[68:71]
	v_mfma_f32_16x16x32_bf16 v[64:67], v[210:213], v[194:197], v[64:67]
	s_barrier
	s_mov_b32 m0, s55
	v_lshl_add_u64 v[138:139], v[138:139], 0, s[24:25]
	global_load_lds_dwordx4 v[138:139], off
	v_lshl_add_u64 v[138:139], v[190:191], 0, s[24:25]
	s_mov_b32 m0, s58
	s_nop 0
	global_load_lds_dwordx4 v[138:139], off
	s_mov_b32 m0, s59
	v_lshl_add_u64 v[138:139], v[214:215], 0, s[24:25]
	ds_read_b128 v[160:163], v141 offset:49152
	ds_read_b128 v[164:167], v141 offset:50176
	ds_read_b128 v[168:171], v141 offset:51200
	ds_read_b128 v[172:175], v141 offset:52224
	ds_read_b128 v[176:179], v141 offset:53248
	ds_read_b128 v[180:183], v141 offset:54272
	ds_read_b128 v[186:189], v141 offset:55296
	ds_read_b128 v[194:197], v141 offset:56320
	global_load_lds_dwordx4 v[138:139], off
	v_lshl_add_u64 v[138:139], v[216:217], 0, s[24:25]
	s_mov_b32 m0, s60
	s_nop 0
	global_load_lds_dwordx4 v[138:139], off
	s_waitcnt vmcnt(6) lgkmcnt(0)
	s_barrier
	s_cbranch_vccnz .Lmskip_94_6
	v_mfma_f32_16x16x32_bf16 v[60:63], v[144:147], v[160:163], v[60:63]
	v_mfma_f32_16x16x32_bf16 v[56:59], v[152:155], v[160:163], v[56:59]
	v_mfma_f32_16x16x32_bf16 v[52:55], v[144:147], v[168:171], v[52:55]
	v_mfma_f32_16x16x32_bf16 v[48:51], v[152:155], v[168:171], v[48:51]
	v_mfma_f32_16x16x32_bf16 v[44:47], v[144:147], v[176:179], v[44:47]
	v_mfma_f32_16x16x32_bf16 v[40:43], v[152:155], v[176:179], v[40:43]
	v_mfma_f32_16x16x32_bf16 v[36:39], v[144:147], v[186:189], v[36:39]
	v_mfma_f32_16x16x32_bf16 v[32:35], v[152:155], v[186:189], v[32:35]
	v_mfma_f32_16x16x32_bf16 v[60:63], v[148:151], v[164:167], v[60:63]
	v_mfma_f32_16x16x32_bf16 v[56:59], v[156:159], v[164:167], v[56:59]
	v_mfma_f32_16x16x32_bf16 v[52:55], v[148:151], v[172:175], v[52:55]
	v_mfma_f32_16x16x32_bf16 v[48:51], v[156:159], v[172:175], v[48:51]
	v_mfma_f32_16x16x32_bf16 v[44:47], v[148:151], v[180:183], v[44:47]
	v_mfma_f32_16x16x32_bf16 v[40:43], v[156:159], v[180:183], v[40:43]
	v_mfma_f32_16x16x32_bf16 v[36:39], v[148:151], v[194:197], v[36:39]
	v_mfma_f32_16x16x32_bf16 v[32:35], v[156:159], v[194:197], v[32:35]
	v_mfma_f32_16x16x32_bf16 v[28:31], v[198:201], v[160:163], v[28:31]
	v_mfma_f32_16x16x32_bf16 v[24:27], v[206:209], v[160:163], v[24:27]
	v_mfma_f32_16x16x32_bf16 v[20:23], v[198:201], v[168:171], v[20:23]
	v_mfma_f32_16x16x32_bf16 v[16:19], v[206:209], v[168:171], v[16:19]
	v_mfma_f32_16x16x32_bf16 v[12:15], v[198:201], v[176:179], v[12:15]
	v_mfma_f32_16x16x32_bf16 v[8:11], v[206:209], v[176:179], v[8:11]
	v_mfma_f32_16x16x32_bf16 v[4:7], v[198:201], v[186:189], v[4:7]
	v_mfma_f32_16x16x32_bf16 v[0:3], v[206:209], v[186:189], v[0:3]
	v_mfma_f32_16x16x32_bf16 v[28:31], v[202:205], v[164:167], v[28:31]
	v_mfma_f32_16x16x32_bf16 v[24:27], v[210:213], v[164:167], v[24:27]
	v_mfma_f32_16x16x32_bf16 v[20:23], v[202:205], v[172:175], v[20:23]
	v_mfma_f32_16x16x32_bf16 v[16:19], v[210:213], v[172:175], v[16:19]
	v_mfma_f32_16x16x32_bf16 v[12:15], v[202:205], v[180:183], v[12:15]
	v_mfma_f32_16x16x32_bf16 v[8:11], v[210:213], v[180:183], v[8:11]
	v_mfma_f32_16x16x32_bf16 v[4:7], v[202:205], v[194:197], v[4:7]
	v_mfma_f32_16x16x32_bf16 v[0:3], v[210:213], v[194:197], v[0:3]

.LBB0_106:
	s_ashr_i32 s26, s20, 31
	v_lshl_add_u64 v[8:9], s[28:29], 0, v[184:185]
	v_mov_b32_e32 v191, v185
	s_lshr_b32 s26, s26, 26
	s_add_i32 s69, s59, 0x18000
	v_lshl_add_u64 v[10:11], s[28:29], 0, v[190:191]
	v_mov_b32_e32 v187, v185
	s_and_b32 s0, s0, 3
	s_add_i32 s26, s20, s26
	v_lshl_add_u64 v[8:9], v[8:9], 0, s[24:25]
	s_mov_b32 m0, s69
	s_add_i32 s70, s59, 0x1a000
	v_lshl_add_u64 v[12:13], s[22:23], 0, v[186:187]
	v_mov_b32_e32 v189, v185
	s_ashr_i32 s34, s26, 6
	s_lshl_b32 s30, s1, 13
	s_lshl_b32 s31, s0, 12
	s_waitcnt vmcnt(2)
	s_barrier
	global_load_lds_dwordx4 v[8:9], off
	v_lshl_add_u64 v[8:9], v[10:11], 0, s[24:25]
	s_mov_b32 m0, s70
	s_add_i32 s71, s59, 0x8000
	s_add_i32 s54, s59, 0xa000
	v_lshl_add_u64 v[14:15], s[22:23], 0, v[188:189]
	global_load_lds_dwordx4 v[8:9], off
	v_lshl_add_u64 v[8:9], v[12:13], 0, s[24:25]
	s_mov_b32 m0, s71
	s_add_u32 s26, s28, 0x10080
	global_load_lds_dwordx4 v[8:9], off
	v_lshl_add_u64 v[8:9], v[14:15], 0, s[24:25]
	s_mov_b32 m0, s54
	s_addc_u32 s27, s29, 0
	s_add_i32 s40, s59, 0x1c000
	global_load_lds_dwordx4 v[8:9], off
	v_lshl_add_u64 v[8:9], s[26:27], 0, v[184:185]
	s_mov_b32 m0, s40
	s_add_i32 s41, s59, 0x1e000
	global_load_lds_dwordx4 v[8:9], off
	v_lshl_add_u64 v[8:9], s[26:27], 0, v[190:191]
	s_mov_b32 m0, s41
	v_bfe_u32 v7, v0, 4, 2
	global_load_lds_dwordx4 v[8:9], off
	v_and_b32_e32 v8, 15, v0
	v_lshlrev_b32_e32 v9, 3, v7
	v_lshlrev_b32_e32 v7, 4, v7
	v_lshl_or_b32 v242, s1, 6, v8
	v_lshl_or_b32 v7, v8, 6, v7
	v_lshlrev_b32_e32 v8, 2, v0
	v_and_b32_e32 v245, 63, v0
	v_lshlrev_b32_e32 v0, 14, v1
	v_and_b32_e32 v0, 0xffff8000, v0
	v_lshl_add_u32 v0, v2, 11, v0
	v_and_b32_e32 v1, 1, v1
	v_lshl_or_b32 v0, v1, 6, v0
	v_lshl_add_u32 v194, v3, 1, v0
	v_lshlrev_b32_e32 v0, 14, v4
	s_cmp_gt_i32 s20, 63
	v_and_b32_e32 v0, 0xffff8000, v0
	s_cselect_b64 s[4:5], -1, 0
	v_lshl_add_u32 v0, v5, 11, v0
	v_and_b32_e32 v1, 1, v4
	v_and_b32_e32 v8, 32, v8
	s_waitcnt vmcnt(6)
	v_writelane_b32 v255, s4, 47
	v_lshl_or_b32 v0, v1, 6, v0
	v_mov_b32_e32 v2, v185
	v_mov_b32_e32 v3, v185
	v_bitop3_b32 v243, v7, s30, v8 bitop3:0xde
	v_bitop3_b32 v244, v7, s31, v8 bitop3:0xde
	v_writelane_b32 v255, s5, 48
	v_lshl_or_b32 v192, s0, 5, v9
	s_lshr_b32 s4, s36, 1
	v_lshl_add_u32 v196, v6, 1, v0
	v_mov_b32_e32 v0, v185
	v_mov_b32_e32 v1, v185
	v_mov_b64_e32 v[10:11], v[2:3]
	v_mov_b64_e32 v[6:7], v[2:3]
	v_mov_b64_e32 v[14:15], v[2:3]
	v_mov_b64_e32 v[18:19], v[2:3]
	v_mov_b64_e32 v[22:23], v[2:3]
	v_mov_b64_e32 v[26:27], v[2:3]
	v_mov_b64_e32 v[30:31], v[2:3]
	v_mov_b64_e32 v[34:35], v[2:3]
	v_mov_b64_e32 v[38:39], v[2:3]
	v_mov_b64_e32 v[42:43], v[2:3]
	v_mov_b64_e32 v[46:47], v[2:3]
	v_mov_b64_e32 v[50:51], v[2:3]
	v_mov_b64_e32 v[54:55], v[2:3]
	v_mov_b64_e32 v[58:59], v[2:3]
	v_mov_b64_e32 v[62:63], v[2:3]
	v_mov_b64_e32 v[66:67], v[2:3]
	v_mov_b64_e32 v[70:71], v[2:3]
	v_mov_b64_e32 v[74:75], v[2:3]
	v_mov_b64_e32 v[78:79], v[2:3]
	v_mov_b64_e32 v[82:83], v[2:3]
	v_mov_b64_e32 v[86:87], v[2:3]
	v_mov_b64_e32 v[90:91], v[2:3]
	v_mov_b64_e32 v[94:95], v[2:3]
	v_mov_b64_e32 v[98:99], v[2:3]
	v_mov_b64_e32 v[110:111], v[2:3]
	v_mov_b64_e32 v[114:115], v[2:3]
	v_mov_b64_e32 v[126:127], v[2:3]
	v_mov_b64_e32 v[130:131], v[2:3]
	v_mov_b64_e32 v[138:139], v[2:3]
	v_mov_b64_e32 v[146:147], v[2:3]
	v_mov_b64_e32 v[150:151], v[2:3]
	s_add_i32 s68, s34, -2
	s_lshl_b32 s20, s1, 2
	s_mov_b32 s1, s89
	v_or_b32_e32 v246, 48, v242
	v_add_u32_e32 v247, 0x80, v242
	v_add_u32_e32 v248, 0x90, v242
	v_add_u32_e32 v249, 0xa0, v242
	v_add_u32_e32 v250, 0xb0, v242
	s_mov_b32 s84, s36
	v_writelane_b32 v255, s4, 49
	v_mov_b32_e32 v195, v185
	v_mov_b32_e32 v197, v185
	s_mov_b32 s26, 0
	v_mov_b64_e32 v[8:9], v[0:1]
	v_mov_b64_e32 v[4:5], v[0:1]
	v_mov_b64_e32 v[12:13], v[0:1]
	v_mov_b64_e32 v[16:17], v[0:1]
	v_mov_b64_e32 v[20:21], v[0:1]
	v_mov_b64_e32 v[24:25], v[0:1]
	v_mov_b64_e32 v[28:29], v[0:1]
	v_mov_b64_e32 v[32:33], v[0:1]
	v_mov_b64_e32 v[36:37], v[0:1]
	v_mov_b64_e32 v[40:41], v[0:1]
	v_mov_b64_e32 v[44:45], v[0:1]
	v_mov_b64_e32 v[48:49], v[0:1]
	v_mov_b64_e32 v[52:53], v[0:1]
	v_mov_b64_e32 v[56:57], v[0:1]
	v_mov_b64_e32 v[60:61], v[0:1]
	v_mov_b64_e32 v[64:65], v[0:1]
	v_mov_b64_e32 v[68:69], v[0:1]
	v_mov_b64_e32 v[72:73], v[0:1]
	v_mov_b64_e32 v[76:77], v[0:1]
	v_mov_b64_e32 v[80:81], v[0:1]
	v_mov_b64_e32 v[84:85], v[0:1]
	v_mov_b64_e32 v[88:89], v[0:1]
	v_mov_b64_e32 v[92:93], v[0:1]
	v_mov_b64_e32 v[96:97], v[0:1]
	v_mov_b64_e32 v[108:109], v[0:1]
	v_mov_b64_e32 v[112:113], v[0:1]
	v_mov_b64_e32 v[124:125], v[0:1]
	v_mov_b64_e32 v[128:129], v[0:1]
	v_mov_b64_e32 v[136:137], v[0:1]
	v_mov_b64_e32 v[144:145], v[0:1]
	v_mov_b64_e32 v[148:149], v[0:1]
	s_mov_b32 s58, 0
	s_barrier
	s_branch .LBB0_108

.LBB0_232:
	v_readlane_b32 s28, v254, 26
	v_mov_b32_e32 v133, v185
	v_readlane_b32 s29, v254, 27
	v_mov_b32_e32 v129, v185
	v_readlane_b32 s22, v254, 22
	v_lshl_add_u64 v[8:9], s[28:29], 0, v[132:133]
	s_add_i32 s46, s38, 0x18000
	v_lshl_add_u64 v[10:11], s[28:29], 0, v[128:129]
	v_mov_b32_e32 v135, v185
	v_readlane_b32 s23, v254, 23
	v_lshl_add_u64 v[8:9], v[8:9], 0, s[24:25]
	s_mov_b32 m0, s46
	s_add_i32 s47, s38, 0x1a000
	v_lshl_add_u64 v[12:13], s[22:23], 0, v[134:135]
	v_mov_b32_e32 v131, v185
	s_waitcnt vmcnt(2)
	s_barrier
	global_load_lds_dwordx4 v[8:9], off
	v_lshl_add_u64 v[8:9], v[10:11], 0, s[24:25]
	s_mov_b32 m0, s47
	s_add_i32 s48, s38, 0x8000
	v_lshl_add_u64 v[14:15], s[22:23], 0, v[130:131]
	global_load_lds_dwordx4 v[8:9], off
	v_lshl_add_u64 v[8:9], v[12:13], 0, s[24:25]
	s_mov_b32 m0, s48
	s_add_i32 s49, s38, 0xa000
	v_readlane_b32 s4, v254, 28
	global_load_lds_dwordx4 v[8:9], off
	v_lshl_add_u64 v[8:9], v[14:15], 0, s[24:25]
	s_mov_b32 m0, s49
	s_add_i32 s50, s38, 0x1c000
	v_readlane_b32 s5, v254, 29
	global_load_lds_dwordx4 v[8:9], off
	s_nop 0
	v_lshl_add_u64 v[8:9], s[4:5], 0, v[132:133]
	s_mov_b32 m0, s50
	s_add_i32 s51, s38, 0x1e000
	global_load_lds_dwordx4 v[8:9], off
	v_lshl_add_u64 v[8:9], s[4:5], 0, v[128:129]
	s_mov_b32 m0, s51
	v_and_b32_e32 v10, 48, v0
	global_load_lds_dwordx4 v[8:9], off
	v_and_b32_e32 v8, 15, v0
	v_lshlrev_b32_e32 v0, 2, v0
	s_and_b32 s0, s0, 3
	v_lshl_or_b32 v7, v8, 6, v10
	s_lshl_b32 s20, s1, 13
	v_and_b32_e32 v0, 32, v0
	v_bitop3_b32 v142, v7, s20, v0 bitop3:0xde
	s_lshl_b32 s20, s0, 12
	v_bitop3_b32 v143, v7, s20, v0 bitop3:0xde
	v_lshlrev_b32_e32 v0, 16, v5
	v_and_b32_e32 v0, 0xfffe0000, v0
	v_lshl_add_u32 v0, v4, 13, v0
	v_and_b32_e32 v4, 1, v5
	v_lshl_or_b32 v0, v4, 6, v0
	v_lshl_add_u32 v136, v6, 1, v0
	v_lshlrev_b32_e32 v0, 16, v1
	s_lshl_b32 s0, s0, 6
	v_and_b32_e32 v0, 0xfffe0000, v0
	s_waitcnt vmcnt(6)
	s_lshl_b32 s52, s1, 2
	s_or_b32 s1, s0, 0x100
	v_lshl_add_u32 v0, v2, 13, v0
	v_and_b32_e32 v1, 1, v1
	v_lshl_or_b32 v0, v1, 6, v0
	s_lshl_b32 s63, s0, 4
	s_lshl_b32 s64, s1, 4
	v_readlane_b32 s0, v254, 18
	v_readlane_b32 s72, v253, 16
	s_add_i32 s53, s52, 8
	s_or_b32 s54, s52, 1
	s_or_b32 s55, s52, 2
	s_or_b32 s58, s52, 3
	s_add_i32 s59, s52, 9
	s_add_i32 s60, s52, 10
	s_add_i32 s61, s52, 11
	v_mov_b32_e32 v137, v185
	v_lshl_add_u32 v138, v3, 1, v0
	v_mov_b32_e32 v139, v185
	s_mov_b32 s62, 0
	v_lshlrev_b32_e32 v184, 4, v10
	v_lshlrev_b32_e32 v140, 4, v8
	s_mov_b32 s71, s0
	v_readlane_b32 s70, v254, 16
	v_readlane_b32 s56, v254, 17
	v_readlane_b32 s78, v253, 22
	v_readlane_b32 s79, v253, 23
	s_barrier
	v_readlane_b32 s1, v254, 19
	v_readlane_b32 s73, v253, 17
	v_readlane_b32 s74, v253, 18
	v_readlane_b32 s75, v253, 19
	v_readlane_b32 s76, v253, 20
	v_readlane_b32 s77, v253, 21
	v_readlane_b32 s80, v253, 24
	v_readlane_b32 s81, v253, 25
	v_readlane_b32 s82, v253, 26
	v_readlane_b32 s83, v253, 27
	v_readlane_b32 s84, v253, 28
	v_readlane_b32 s85, v253, 29
	v_readlane_b32 s86, v253, 30
	v_readlane_b32 s87, v253, 31
.LBB0_233:
	s_add_i32 s62, s62, 1
	s_waitcnt lgkmcnt(0)
	s_mul_i32 s0, s62, s90
	s_mov_b64 s[26:27], s[22:23]
	s_add_i32 s22, s0, s96
	s_cmpk_lt_i32 s22, 0x100
	s_cselect_b64 s[30:31], -1, 0
	s_cmpk_gt_i32 s22, 0xff
	s_mov_b64 s[34:35], s[28:29]
	s_mov_b32 s20, s69
	s_mov_b32 s29, s68
	s_mov_b32 s28, s65
	s_cselect_b64 s[0:1], -1, 0
	s_and_b32 s68, s22, 3
	s_bfe_u32 s69, s22, 0x30002
	s_ashr_i32 s65, s22, 5
	s_and_b64 s[22:23], s[30:31], exec
	s_cselect_b32 s29, s68, s29
	s_cselect_b32 s28, s65, s28
	s_cselect_b32 s22, s69, s20
	s_lshl_b32 s36, s29, 10
	s_ashr_i32 s23, s22, 31
	s_ashr_i32 s37, s36, 31
	v_readlane_b32 s4, v253, 0
	s_lshl_b64 s[22:23], s[22:23], 21
	s_lshl_b64 s[36:37], s[36:37], 1
	v_readlane_b32 s16, v253, 12
	v_readlane_b32 s17, v253, 13
	s_add_u32 s20, s16, s22
	s_addc_u32 s23, s17, s23
	s_add_u32 s22, s20, s36
	s_addc_u32 s23, s23, s37
	s_and_b64 vcc, s[30:31], exec
	s_cselect_b32 vcc_lo, s23, s27
	s_cselect_b32 vcc_hi, s22, s26
	s_ashr_i32 s29, s28, 31
	s_lshl_b64 s[28:29], s[28:29], 13
	s_add_u32 s20, s78, s28
	s_addc_u32 s29, s79, s29
	s_add_u32 s28, s20, s36
	s_addc_u32 s29, s29, s37
	s_and_b64 s[30:31], s[30:31], exec
	s_cselect_b32 s33, s29, s35
	s_cselect_b32 s20, s28, s34
	s_add_u32 s30, s26, 0x100080
	s_addc_u32 s31, s27, 0
	s_add_u32 s26, s34, 0x100
	v_mov_b32_e32 v0, 0
	s_addc_u32 s27, s35, 0
	s_mov_b32 s96, -2
	v_mov_b32_e32 v1, v0
	v_mov_b32_e32 v2, v0
	v_mov_b32_e32 v3, v0
	v_mov_b32_e32 v4, v0
	v_mov_b32_e32 v5, v0
	v_mov_b32_e32 v6, v0
	v_mov_b32_e32 v7, v0
	v_mov_b32_e32 v8, v0
	v_mov_b32_e32 v9, v0
	v_mov_b32_e32 v10, v0
	v_mov_b32_e32 v11, v0
	v_mov_b32_e32 v12, v0
	v_mov_b32_e32 v13, v0
	v_mov_b32_e32 v14, v0
	v_mov_b32_e32 v15, v0
	v_mov_b32_e32 v16, v0
	v_mov_b32_e32 v17, v0
	v_mov_b32_e32 v18, v0
	v_mov_b32_e32 v19, v0
	v_mov_b32_e32 v20, v0
	v_mov_b32_e32 v21, v0
	v_mov_b32_e32 v22, v0
	v_mov_b32_e32 v23, v0
	v_mov_b32_e32 v24, v0
	v_mov_b32_e32 v25, v0
	v_mov_b32_e32 v26, v0
	v_mov_b32_e32 v27, v0
	v_mov_b32_e32 v28, v0
	v_mov_b32_e32 v29, v0
	v_mov_b32_e32 v30, v0
	v_mov_b32_e32 v31, v0
	v_mov_b32_e32 v32, v0
	v_mov_b32_e32 v33, v0
	v_mov_b32_e32 v34, v0
	v_mov_b32_e32 v35, v0
	v_mov_b32_e32 v36, v0
	v_mov_b32_e32 v37, v0
	v_mov_b32_e32 v38, v0
	v_mov_b32_e32 v39, v0
	v_mov_b32_e32 v40, v0
	v_mov_b32_e32 v41, v0
	v_mov_b32_e32 v42, v0
	v_mov_b32_e32 v43, v0
	v_mov_b32_e32 v44, v0
	v_mov_b32_e32 v45, v0
	v_mov_b32_e32 v46, v0
	v_mov_b32_e32 v47, v0
	v_mov_b32_e32 v48, v0
	v_mov_b32_e32 v49, v0
	v_mov_b32_e32 v50, v0
	v_mov_b32_e32 v51, v0
	v_mov_b32_e32 v52, v0
	v_mov_b32_e32 v53, v0
	v_mov_b32_e32 v54, v0
	v_mov_b32_e32 v55, v0
	v_mov_b32_e32 v56, v0
	v_mov_b32_e32 v57, v0
	v_mov_b32_e32 v58, v0
	v_mov_b32_e32 v59, v0
	v_mov_b32_e32 v60, v0
	v_mov_b32_e32 v61, v0
	v_mov_b32_e32 v62, v0
	v_mov_b32_e32 v63, v0
	v_mov_b32_e32 v64, v0
	v_mov_b32_e32 v65, v0
	v_mov_b32_e32 v66, v0
	v_mov_b32_e32 v67, v0
	v_mov_b32_e32 v68, v0
	v_mov_b32_e32 v69, v0
	v_mov_b32_e32 v70, v0
	v_mov_b32_e32 v71, v0
	v_mov_b32_e32 v72, v0
	v_mov_b32_e32 v73, v0
	v_mov_b32_e32 v74, v0
	v_mov_b32_e32 v75, v0
	v_mov_b32_e32 v76, v0
	v_mov_b32_e32 v77, v0
	v_mov_b32_e32 v78, v0
	v_mov_b32_e32 v79, v0
	v_mov_b32_e32 v80, v0
	v_mov_b32_e32 v81, v0
	v_mov_b32_e32 v82, v0
	v_mov_b32_e32 v83, v0
	v_mov_b32_e32 v84, v0
	v_mov_b32_e32 v85, v0
	v_mov_b32_e32 v86, v0
	v_mov_b32_e32 v87, v0
	v_mov_b32_e32 v88, v0
	v_mov_b32_e32 v89, v0
	v_mov_b32_e32 v90, v0
	v_mov_b32_e32 v91, v0
	v_mov_b32_e32 v92, v0
	v_mov_b32_e32 v93, v0
	v_mov_b32_e32 v94, v0
	v_mov_b32_e32 v95, v0
	v_mov_b32_e32 v96, v0
	v_mov_b32_e32 v97, v0
	v_mov_b32_e32 v98, v0
	v_mov_b32_e32 v99, v0
	v_mov_b32_e32 v100, v0
	v_mov_b32_e32 v101, v0
	v_mov_b32_e32 v102, v0
	v_mov_b32_e32 v103, v0
	v_mov_b32_e32 v104, v0
	v_mov_b32_e32 v105, v0
	v_mov_b32_e32 v106, v0
	v_mov_b32_e32 v107, v0
	v_mov_b32_e32 v108, v0
	v_mov_b32_e32 v109, v0
	v_mov_b32_e32 v110, v0
	v_mov_b32_e32 v111, v0
	v_mov_b32_e32 v112, v0
	v_mov_b32_e32 v113, v0
	v_mov_b32_e32 v114, v0
	v_mov_b32_e32 v115, v0
	v_mov_b32_e32 v116, v0
	v_mov_b32_e32 v117, v0
	v_mov_b32_e32 v118, v0
	v_mov_b32_e32 v119, v0
	v_mov_b32_e32 v120, v0
	v_mov_b32_e32 v121, v0
	v_mov_b32_e32 v122, v0
	v_mov_b32_e32 v123, v0
	v_mov_b32_e32 v124, v0
	v_mov_b32_e32 v125, v0
	v_mov_b32_e32 v126, v0
	v_mov_b32_e32 v127, v0
	v_readlane_b32 s5, v253, 1
	v_readlane_b32 s6, v253, 2
	v_readlane_b32 s7, v253, 3
	v_readlane_b32 s8, v253, 4
	v_readlane_b32 s9, v253, 5
	v_readlane_b32 s10, v253, 6
	v_readlane_b32 s11, v253, 7
	v_readlane_b32 s12, v253, 8
	v_readlane_b32 s13, v253, 9
	v_readlane_b32 s14, v253, 10
	v_readlane_b32 s15, v253, 11
	v_readlane_b32 s18, v253, 14
	v_readlane_b32 s19, v253, 15
	v_add_u32_e32 v230, 0x10000, v143
.LBB0_234:
	ds_read_b128 v[144:147], v230
	ds_read_b128 v[148:151], v230 offset:1024
	ds_read_b128 v[152:155], v230 offset:2048
	ds_read_b128 v[156:159], v230 offset:3072
	s_add_u32 s34, s30, 0xfff00080
	s_addc_u32 s35, s31, -1
	s_cmp_eq_u32 s96, 12
	s_cselect_b32 s37, vcc_lo, s35
	s_cselect_b32 s36, vcc_hi, s34
	s_cselect_b32 s35, s33, s27
	s_cselect_b32 s34, s20, s26
	v_lshl_add_u64 v[190:191], s[30:31], 0, v[136:137]
	s_add_i32 m0, s38, 0xc000
	ds_read_b128 v[160:163], v142
	ds_read_b128 v[164:167], v142 offset:1024
	ds_read_b128 v[168:171], v142 offset:2048
	ds_read_b128 v[172:175], v142 offset:3072
	ds_read_b128 v[176:179], v142 offset:4096
	ds_read_b128 v[180:183], v142 offset:5120
	ds_read_b128 v[186:189], v142 offset:6144
	ds_read_b128 v[194:197], v142 offset:7168
	global_load_lds_dwordx4 v[190:191], off
	v_lshl_add_u64 v[190:191], s[30:31], 0, v[138:139]
	s_add_i32 m0, s38, 0xe000
	s_nop 0
	global_load_lds_dwordx4 v[190:191], off
	ds_read_b128 v[198:201], v230 offset:16384
	ds_read_b128 v[202:205], v230 offset:17408
	ds_read_b128 v[206:209], v230 offset:18432
	ds_read_b128 v[210:213], v230 offset:19456
	s_waitcnt vmcnt(8) lgkmcnt(0)
	s_barrier
	v_mfma_f32_16x16x32_bf16 v[124:127], v[144:147], v[160:163], v[124:127]
	v_mfma_f32_16x16x32_bf16 v[120:123], v[152:155], v[160:163], v[120:123]
	v_mfma_f32_16x16x32_bf16 v[116:119], v[144:147], v[168:171], v[116:119]
	v_mfma_f32_16x16x32_bf16 v[112:115], v[152:155], v[168:171], v[112:115]
	v_mfma_f32_16x16x32_bf16 v[108:111], v[144:147], v[176:179], v[108:111]
	v_mfma_f32_16x16x32_bf16 v[104:107], v[152:155], v[176:179], v[104:107]
	v_mfma_f32_16x16x32_bf16 v[100:103], v[144:147], v[186:189], v[100:103]
	v_mfma_f32_16x16x32_bf16 v[96:99], v[152:155], v[186:189], v[96:99]
	v_mfma_f32_16x16x32_bf16 v[124:127], v[148:151], v[164:167], v[124:127]
	v_mfma_f32_16x16x32_bf16 v[120:123], v[156:159], v[164:167], v[120:123]
	v_mfma_f32_16x16x32_bf16 v[116:119], v[148:151], v[172:175], v[116:119]
	v_mfma_f32_16x16x32_bf16 v[112:115], v[156:159], v[172:175], v[112:115]
	v_mfma_f32_16x16x32_bf16 v[108:111], v[148:151], v[180:183], v[108:111]
	v_mfma_f32_16x16x32_bf16 v[104:107], v[156:159], v[180:183], v[104:107]
	v_mfma_f32_16x16x32_bf16 v[100:103], v[148:151], v[194:197], v[100:103]
	v_mfma_f32_16x16x32_bf16 v[96:99], v[156:159], v[194:197], v[96:99]
	v_mfma_f32_16x16x32_bf16 v[92:95], v[198:201], v[160:163], v[92:95]
	v_mfma_f32_16x16x32_bf16 v[88:91], v[206:209], v[160:163], v[88:91]
	v_mfma_f32_16x16x32_bf16 v[84:87], v[198:201], v[168:171], v[84:87]
	v_mfma_f32_16x16x32_bf16 v[80:83], v[206:209], v[168:171], v[80:83]
	v_mfma_f32_16x16x32_bf16 v[76:79], v[198:201], v[176:179], v[76:79]
	v_mfma_f32_16x16x32_bf16 v[72:75], v[206:209], v[176:179], v[72:75]
	v_mfma_f32_16x16x32_bf16 v[68:71], v[198:201], v[186:189], v[68:71]
	v_mfma_f32_16x16x32_bf16 v[64:67], v[206:209], v[186:189], v[64:67]
	v_mfma_f32_16x16x32_bf16 v[92:95], v[202:205], v[164:167], v[92:95]
	v_mfma_f32_16x16x32_bf16 v[88:91], v[210:213], v[164:167], v[88:91]
	v_mfma_f32_16x16x32_bf16 v[84:87], v[202:205], v[172:175], v[84:87]
	v_mfma_f32_16x16x32_bf16 v[80:83], v[210:213], v[172:175], v[80:83]
	v_mfma_f32_16x16x32_bf16 v[76:79], v[202:205], v[180:183], v[76:79]
	v_mfma_f32_16x16x32_bf16 v[72:75], v[210:213], v[180:183], v[72:75]
	v_mfma_f32_16x16x32_bf16 v[68:71], v[202:205], v[194:197], v[68:71]
	v_mfma_f32_16x16x32_bf16 v[64:67], v[210:213], v[194:197], v[64:67]
	s_barrier
	s_mov_b32 m0, s39
	v_lshl_add_u64 v[190:191], s[34:35], 0, v[132:133]
	global_load_lds_dwordx4 v[190:191], off
	v_lshl_add_u64 v[214:215], s[34:35], 0, v[128:129]
	s_mov_b32 m0, s40
	s_nop 0
	global_load_lds_dwordx4 v[214:215], off
	s_mov_b32 m0, s38
	v_lshl_add_u64 v[216:217], s[36:37], 0, v[134:135]
	ds_read_b128 v[160:163], v142 offset:16384
	ds_read_b128 v[164:167], v142 offset:17408
	ds_read_b128 v[168:171], v142 offset:18432
	ds_read_b128 v[172:175], v142 offset:19456
	ds_read_b128 v[176:179], v142 offset:20480
	ds_read_b128 v[180:183], v142 offset:21504
	ds_read_b128 v[186:189], v142 offset:22528
	ds_read_b128 v[194:197], v142 offset:23552
	global_load_lds_dwordx4 v[216:217], off
	v_lshl_add_u64 v[242:243], s[36:37], 0, v[130:131]
	s_mov_b32 m0, s41
	s_nop 0
	global_load_lds_dwordx4 v[242:243], off
	s_waitcnt vmcnt(6) lgkmcnt(0)
	s_barrier
	v_mfma_f32_16x16x32_bf16 v[60:63], v[144:147], v[160:163], v[60:63]
	v_mfma_f32_16x16x32_bf16 v[56:59], v[152:155], v[160:163], v[56:59]
	v_mfma_f32_16x16x32_bf16 v[52:55], v[144:147], v[168:171], v[52:55]
	v_mfma_f32_16x16x32_bf16 v[48:51], v[152:155], v[168:171], v[48:51]
	v_mfma_f32_16x16x32_bf16 v[44:47], v[144:147], v[176:179], v[44:47]
	v_mfma_f32_16x16x32_bf16 v[40:43], v[152:155], v[176:179], v[40:43]
	v_mfma_f32_16x16x32_bf16 v[36:39], v[144:147], v[186:189], v[36:39]
	v_mfma_f32_16x16x32_bf16 v[32:35], v[152:155], v[186:189], v[32:35]
	v_mfma_f32_16x16x32_bf16 v[60:63], v[148:151], v[164:167], v[60:63]
	v_mfma_f32_16x16x32_bf16 v[56:59], v[156:159], v[164:167], v[56:59]
	v_mfma_f32_16x16x32_bf16 v[52:55], v[148:151], v[172:175], v[52:55]
	v_mfma_f32_16x16x32_bf16 v[48:51], v[156:159], v[172:175], v[48:51]
	v_mfma_f32_16x16x32_bf16 v[44:47], v[148:151], v[180:183], v[44:47]
	v_mfma_f32_16x16x32_bf16 v[40:43], v[156:159], v[180:183], v[40:43]
	v_mfma_f32_16x16x32_bf16 v[36:39], v[148:151], v[194:197], v[36:39]
	v_mfma_f32_16x16x32_bf16 v[32:35], v[156:159], v[194:197], v[32:35]
	v_mfma_f32_16x16x32_bf16 v[28:31], v[198:201], v[160:163], v[28:31]
	v_mfma_f32_16x16x32_bf16 v[24:27], v[206:209], v[160:163], v[24:27]
	v_mfma_f32_16x16x32_bf16 v[20:23], v[198:201], v[168:171], v[20:23]
	v_mfma_f32_16x16x32_bf16 v[16:19], v[206:209], v[168:171], v[16:19]
	v_mfma_f32_16x16x32_bf16 v[12:15], v[198:201], v[176:179], v[12:15]
	v_mfma_f32_16x16x32_bf16 v[8:11], v[206:209], v[176:179], v[8:11]
	v_mfma_f32_16x16x32_bf16 v[4:7], v[198:201], v[186:189], v[4:7]
	v_mfma_f32_16x16x32_bf16 v[0:3], v[206:209], v[186:189], v[0:3]
	v_mfma_f32_16x16x32_bf16 v[28:31], v[202:205], v[164:167], v[28:31]
	v_mfma_f32_16x16x32_bf16 v[24:27], v[210:213], v[164:167], v[24:27]
	v_mfma_f32_16x16x32_bf16 v[20:23], v[202:205], v[172:175], v[20:23]
	v_mfma_f32_16x16x32_bf16 v[16:19], v[210:213], v[172:175], v[16:19]
	v_mfma_f32_16x16x32_bf16 v[12:15], v[202:205], v[180:183], v[12:15]
	v_mfma_f32_16x16x32_bf16 v[8:11], v[210:213], v[180:183], v[8:11]
	v_mfma_f32_16x16x32_bf16 v[4:7], v[202:205], v[194:197], v[4:7]
	v_mfma_f32_16x16x32_bf16 v[0:3], v[210:213], v[194:197], v[0:3]
	s_barrier
	s_add_u32 s66, s34, 0x800000
	s_addc_u32 s67, s35, 0
	s_mov_b32 m0, s42
	v_lshl_add_u64 v[144:145], s[66:67], 0, v[132:133]
	global_load_lds_dwordx4 v[144:145], off
	v_lshl_add_u64 v[144:145], s[66:67], 0, v[128:129]
	s_mov_b32 m0, s43
	s_nop 0
	global_load_lds_dwordx4 v[144:145], off
	ds_read_b128 v[144:147], v230 offset:32768
	ds_read_b128 v[148:151], v230 offset:33792
	ds_read_b128 v[152:155], v230 offset:34816
	ds_read_b128 v[156:159], v230 offset:35840
	s_add_u32 s36, s36, 0x100000
	s_addc_u32 s37, s37, 0
	s_mov_b32 m0, s44
	v_lshl_add_u64 v[198:199], s[36:37], 0, v[134:135]
	ds_read_b128 v[160:163], v142 offset:32768
	ds_read_b128 v[164:167], v142 offset:33792
	ds_read_b128 v[168:171], v142 offset:34816
	ds_read_b128 v[172:175], v142 offset:35840
	ds_read_b128 v[176:179], v142 offset:36864
	ds_read_b128 v[180:183], v142 offset:37888
	ds_read_b128 v[186:189], v142 offset:38912
	ds_read_b128 v[194:197], v142 offset:39936
	global_load_lds_dwordx4 v[198:199], off
	v_lshl_add_u64 v[198:199], s[36:37], 0, v[130:131]
	s_mov_b32 m0, s45
	s_nop 0
	global_load_lds_dwordx4 v[198:199], off
	ds_read_b128 v[198:201], v230 offset:49152
	ds_read_b128 v[202:205], v230 offset:50176
	ds_read_b128 v[206:209], v230 offset:51200
	ds_read_b128 v[210:213], v230 offset:52224
	s_waitcnt vmcnt(8) lgkmcnt(0)
	s_barrier
	v_mfma_f32_16x16x32_bf16 v[124:127], v[144:147], v[160:163], v[124:127]
	v_mfma_f32_16x16x32_bf16 v[120:123], v[152:155], v[160:163], v[120:123]
	v_mfma_f32_16x16x32_bf16 v[116:119], v[144:147], v[168:171], v[116:119]
	v_mfma_f32_16x16x32_bf16 v[112:115], v[152:155], v[168:171], v[112:115]
	v_mfma_f32_16x16x32_bf16 v[108:111], v[144:147], v[176:179], v[108:111]
	v_mfma_f32_16x16x32_bf16 v[104:107], v[152:155], v[176:179], v[104:107]
	v_mfma_f32_16x16x32_bf16 v[100:103], v[144:147], v[186:189], v[100:103]
	v_mfma_f32_16x16x32_bf16 v[96:99], v[152:155], v[186:189], v[96:99]
	v_mfma_f32_16x16x32_bf16 v[124:127], v[148:151], v[164:167], v[124:127]
	v_mfma_f32_16x16x32_bf16 v[120:123], v[156:159], v[164:167], v[120:123]
	v_mfma_f32_16x16x32_bf16 v[116:119], v[148:151], v[172:175], v[116:119]
	v_mfma_f32_16x16x32_bf16 v[112:115], v[156:159], v[172:175], v[112:115]
	v_mfma_f32_16x16x32_bf16 v[108:111], v[148:151], v[180:183], v[108:111]
	v_mfma_f32_16x16x32_bf16 v[104:107], v[156:159], v[180:183], v[104:107]
	v_mfma_f32_16x16x32_bf16 v[100:103], v[148:151], v[194:197], v[100:103]
	v_mfma_f32_16x16x32_bf16 v[96:99], v[156:159], v[194:197], v[96:99]
	v_mfma_f32_16x16x32_bf16 v[92:95], v[198:201], v[160:163], v[92:95]
	v_mfma_f32_16x16x32_bf16 v[88:91], v[206:209], v[160:163], v[88:91]
	v_mfma_f32_16x16x32_bf16 v[84:87], v[198:201], v[168:171], v[84:87]
	v_mfma_f32_16x16x32_bf16 v[80:83], v[206:209], v[168:171], v[80:83]
	v_mfma_f32_16x16x32_bf16 v[76:79], v[198:201], v[176:179], v[76:79]
	v_mfma_f32_16x16x32_bf16 v[72:75], v[206:209], v[176:179], v[72:75]
	v_mfma_f32_16x16x32_bf16 v[68:71], v[198:201], v[186:189], v[68:71]
	v_mfma_f32_16x16x32_bf16 v[64:67], v[206:209], v[186:189], v[64:67]
	v_mfma_f32_16x16x32_bf16 v[92:95], v[202:205], v[164:167], v[92:95]
	v_mfma_f32_16x16x32_bf16 v[88:91], v[210:213], v[164:167], v[88:91]
	v_mfma_f32_16x16x32_bf16 v[84:87], v[202:205], v[172:175], v[84:87]
	v_mfma_f32_16x16x32_bf16 v[80:83], v[210:213], v[172:175], v[80:83]
	v_mfma_f32_16x16x32_bf16 v[76:79], v[202:205], v[180:183], v[76:79]
	v_mfma_f32_16x16x32_bf16 v[72:75], v[210:213], v[180:183], v[72:75]
	v_mfma_f32_16x16x32_bf16 v[68:71], v[202:205], v[194:197], v[68:71]
	v_mfma_f32_16x16x32_bf16 v[64:67], v[210:213], v[194:197], v[64:67]
	s_barrier
	s_mov_b32 m0, s46
	v_lshl_add_u64 v[190:191], v[190:191], 0, s[24:25]
	global_load_lds_dwordx4 v[190:191], off
	v_lshl_add_u64 v[190:191], v[214:215], 0, s[24:25]
	s_mov_b32 m0, s47
	s_nop 0
	global_load_lds_dwordx4 v[190:191], off
	s_mov_b32 m0, s48
	v_lshl_add_u64 v[190:191], v[216:217], 0, s[24:25]
	ds_read_b128 v[160:163], v142 offset:49152
	ds_read_b128 v[164:167], v142 offset:50176
	ds_read_b128 v[168:171], v142 offset:51200
	ds_read_b128 v[172:175], v142 offset:52224
	ds_read_b128 v[176:179], v142 offset:53248
	ds_read_b128 v[180:183], v142 offset:54272
	ds_read_b128 v[186:189], v142 offset:55296
	ds_read_b128 v[194:197], v142 offset:56320
	global_load_lds_dwordx4 v[190:191], off
	v_lshl_add_u64 v[190:191], v[242:243], 0, s[24:25]
	s_mov_b32 m0, s49
	s_nop 0
	global_load_lds_dwordx4 v[190:191], off
	s_waitcnt vmcnt(6) lgkmcnt(0)
	s_barrier
	v_mfma_f32_16x16x32_bf16 v[60:63], v[144:147], v[160:163], v[60:63]
	v_mfma_f32_16x16x32_bf16 v[56:59], v[152:155], v[160:163], v[56:59]
	v_mfma_f32_16x16x32_bf16 v[52:55], v[144:147], v[168:171], v[52:55]
	v_mfma_f32_16x16x32_bf16 v[48:51], v[152:155], v[168:171], v[48:51]
	v_mfma_f32_16x16x32_bf16 v[44:47], v[144:147], v[176:179], v[44:47]
	v_mfma_f32_16x16x32_bf16 v[40:43], v[152:155], v[176:179], v[40:43]
	v_mfma_f32_16x16x32_bf16 v[36:39], v[144:147], v[186:189], v[36:39]
	v_mfma_f32_16x16x32_bf16 v[32:35], v[152:155], v[186:189], v[32:35]
	v_mfma_f32_16x16x32_bf16 v[60:63], v[148:151], v[164:167], v[60:63]
	v_mfma_f32_16x16x32_bf16 v[56:59], v[156:159], v[164:167], v[56:59]
	v_mfma_f32_16x16x32_bf16 v[52:55], v[148:151], v[172:175], v[52:55]
	v_mfma_f32_16x16x32_bf16 v[48:51], v[156:159], v[172:175], v[48:51]
	v_mfma_f32_16x16x32_bf16 v[44:47], v[148:151], v[180:183], v[44:47]
	v_mfma_f32_16x16x32_bf16 v[40:43], v[156:159], v[180:183], v[40:43]
	v_mfma_f32_16x16x32_bf16 v[36:39], v[148:151], v[194:197], v[36:39]
	v_mfma_f32_16x16x32_bf16 v[32:35], v[156:159], v[194:197], v[32:35]
	v_mfma_f32_16x16x32_bf16 v[28:31], v[198:201], v[160:163], v[28:31]
	v_mfma_f32_16x16x32_bf16 v[24:27], v[206:209], v[160:163], v[24:27]
	v_mfma_f32_16x16x32_bf16 v[20:23], v[198:201], v[168:171], v[20:23]
	v_mfma_f32_16x16x32_bf16 v[16:19], v[206:209], v[168:171], v[16:19]
	v_mfma_f32_16x16x32_bf16 v[12:15], v[198:201], v[176:179], v[12:15]
	v_mfma_f32_16x16x32_bf16 v[8:11], v[206:209], v[176:179], v[8:11]
	v_mfma_f32_16x16x32_bf16 v[4:7], v[198:201], v[186:189], v[4:7]
	v_mfma_f32_16x16x32_bf16 v[0:3], v[206:209], v[186:189], v[0:3]
	v_mfma_f32_16x16x32_bf16 v[28:31], v[202:205], v[164:167], v[28:31]
	v_mfma_f32_16x16x32_bf16 v[24:27], v[210:213], v[164:167], v[24:27]
	v_mfma_f32_16x16x32_bf16 v[20:23], v[202:205], v[172:175], v[20:23]
	v_mfma_f32_16x16x32_bf16 v[16:19], v[210:213], v[172:175], v[16:19]
	v_mfma_f32_16x16x32_bf16 v[12:15], v[202:205], v[180:183], v[12:15]
	v_mfma_f32_16x16x32_bf16 v[8:11], v[210:213], v[180:183], v[8:11]
	v_mfma_f32_16x16x32_bf16 v[4:7], v[202:205], v[194:197], v[4:7]
	v_mfma_f32_16x16x32_bf16 v[0:3], v[210:213], v[194:197], v[0:3]
	s_barrier
	s_add_u32 s34, s34, 0x800080
	s_addc_u32 s35, s35, 0
	s_mov_b32 m0, s50
	v_lshl_add_u64 v[144:145], s[34:35], 0, v[132:133]
	global_load_lds_dwordx4 v[144:145], off
	v_lshl_add_u64 v[144:145], s[34:35], 0, v[128:129]
	s_mov_b32 m0, s51
	s_nop 0
	global_load_lds_dwordx4 v[144:145], off
	s_add_i32 s96, s96, 2
	s_add_u32 s30, s30, 0x100
	s_addc_u32 s31, s31, 0
	s_add_u32 s26, s26, 0x100
	s_addc_u32 s27, s27, 0
	s_cmp_gt_u32 s96, 13
	s_cbranch_scc0 .LBB0_234
	s_lshl_b32 s20, s71, 7
	s_lshl_b32 s26, s56, 4
	s_or_b32 s27, s26, s20
	s_add_i32 s34, s27, s52
	s_lshl_b32 s88, s70, 19
	v_readlane_b32 s72, v253, 16
	s_ashr_i32 s35, s34, 31
	s_lshl_b64 s[30:31], s[88:89], 4
	v_readlane_b32 s74, v253, 18
	v_readlane_b32 s75, v253, 19
	s_add_u32 s27, s74, s30
	s_addc_u32 s30, s75, s31
	s_lshl_b64 s[34:35], s[34:35], 13
	s_add_u32 s31, s27, s34
	s_addc_u32 s33, s30, s35
	s_add_u32 s34, s31, s63
	s_addc_u32 s35, s33, 0
	v_cvt_pk_bf16_f32 v124, v124, v125
	v_cvt_pk_bf16_f32 v125, v126, v127
	v_cvt_pk_bf16_f32 v126, v120, v121
	v_lshl_add_u64 v[120:121], s[34:35], 0, v[184:185]
	s_add_i32 s34, s54, s20
	s_add_i32 s34, s34, s26
	s_ashr_i32 s35, s34, 31
	s_lshl_b64 s[34:35], s[34:35], 13
	s_add_u32 s36, s27, s34
	s_addc_u32 s37, s30, s35
	s_add_u32 s34, s36, s63
	s_addc_u32 s35, s37, 0
	v_cvt_pk_bf16_f32 v116, v116, v117
	v_cvt_pk_bf16_f32 v117, v118, v119
	v_cvt_pk_bf16_f32 v118, v112, v113
	v_lshl_add_u64 v[112:113], s[34:35], 0, v[184:185]
	s_add_i32 s34, s55, s20
	s_add_i32 s34, s34, s26
	s_ashr_i32 s35, s34, 31
	s_lshl_b64 s[34:35], s[34:35], 13
	s_add_u32 s66, s27, s34
	s_addc_u32 s67, s30, s35
	s_add_u32 s34, s66, s63
	s_addc_u32 s35, s67, 0
	v_cvt_pk_bf16_f32 v108, v108, v109
	v_cvt_pk_bf16_f32 v109, v110, v111
	v_cvt_pk_bf16_f32 v110, v104, v105
	v_lshl_add_u64 v[104:105], s[34:35], 0, v[184:185]
	s_add_i32 s34, s58, s20
	s_add_i32 s34, s34, s26
	s_ashr_i32 s35, s34, 31
	s_lshl_b64 s[34:35], s[34:35], 13
	s_add_u32 s70, s27, s34
	s_addc_u32 s71, s30, s35
	s_add_u32 s34, s70, s63
	s_addc_u32 s35, s71, 0
	v_cvt_pk_bf16_f32 v100, v100, v101
	v_cvt_pk_bf16_f32 v101, v102, v103
	v_cvt_pk_bf16_f32 v102, v96, v97
	v_lshl_add_u64 v[96:97], s[34:35], 0, v[184:185]
	s_add_u32 s34, s31, s64
	s_addc_u32 s35, s33, 0
	v_cvt_pk_bf16_f32 v92, v92, v93
	v_cvt_pk_bf16_f32 v93, v94, v95
	v_cvt_pk_bf16_f32 v94, v88, v89
	v_lshl_add_u64 v[88:89], s[34:35], 0, v[184:185]
	s_add_u32 s34, s36, s64
	s_addc_u32 s35, s37, 0
	v_cvt_pk_bf16_f32 v84, v84, v85
	v_cvt_pk_bf16_f32 v85, v86, v87
	v_cvt_pk_bf16_f32 v86, v80, v81
	v_lshl_add_u64 v[80:81], s[34:35], 0, v[184:185]
	s_add_u32 s34, s66, s64
	s_addc_u32 s35, s67, 0
	v_cvt_pk_bf16_f32 v76, v76, v77
	v_cvt_pk_bf16_f32 v77, v78, v79
	v_cvt_pk_bf16_f32 v78, v72, v73
	v_lshl_add_u64 v[72:73], s[34:35], 0, v[184:185]
	s_add_u32 s34, s70, s64
	s_addc_u32 s35, s71, 0
	s_add_i32 s31, s53, s20
	v_cvt_pk_bf16_f32 v68, v68, v69
	v_cvt_pk_bf16_f32 v69, v70, v71
	v_cvt_pk_bf16_f32 v70, v64, v65
	v_lshl_add_u64 v[64:65], s[34:35], 0, v[184:185]
	s_add_i32 s34, s31, s26
	s_ashr_i32 s35, s34, 31
	s_lshl_b64 s[34:35], s[34:35], 13
	s_add_u32 s31, s27, s34
	s_addc_u32 s33, s30, s35
	s_add_u32 s34, s31, s63
	s_addc_u32 s35, s33, 0
	v_cvt_pk_bf16_f32 v60, v60, v61
	v_cvt_pk_bf16_f32 v61, v62, v63
	v_cvt_pk_bf16_f32 v62, v56, v57
	v_lshl_add_u64 v[56:57], s[34:35], 0, v[184:185]
	s_add_i32 s34, s59, s20
	s_add_i32 s34, s34, s26
	s_ashr_i32 s35, s34, 31
	s_lshl_b64 s[34:35], s[34:35], 13
	s_add_u32 s36, s27, s34
	s_addc_u32 s37, s30, s35
	s_add_u32 s34, s36, s63
	s_addc_u32 s35, s37, 0
	v_cvt_pk_bf16_f32 v52, v52, v53
	v_cvt_pk_bf16_f32 v53, v54, v55
	v_cvt_pk_bf16_f32 v54, v48, v49
	v_lshl_add_u64 v[48:49], s[34:35], 0, v[184:185]
	s_add_i32 s34, s60, s20
	s_add_i32 s34, s34, s26
	s_ashr_i32 s35, s34, 31
	s_lshl_b64 s[34:35], s[34:35], 13
	s_add_u32 s66, s27, s34
	s_addc_u32 s67, s30, s35
	s_add_u32 s34, s66, s63
	s_addc_u32 s35, s67, 0
	s_add_i32 s20, s61, s20
	v_cvt_pk_bf16_f32 v44, v44, v45
	v_cvt_pk_bf16_f32 v45, v46, v47
	v_cvt_pk_bf16_f32 v46, v40, v41
	v_lshl_add_u64 v[40:41], s[34:35], 0, v[184:185]
	s_add_i32 s34, s20, s26
	s_ashr_i32 s35, s34, 31
	s_lshl_b64 s[34:35], s[34:35], 13
	s_add_u32 s20, s27, s34
	s_addc_u32 s30, s30, s35
	s_add_u32 s26, s20, s63
	s_addc_u32 s27, s30, 0
	v_cvt_pk_bf16_f32 v36, v36, v37
	v_cvt_pk_bf16_f32 v37, v38, v39
	v_cvt_pk_bf16_f32 v38, v32, v33
	v_lshl_add_u64 v[32:33], s[26:27], 0, v[184:185]
	s_add_u32 s26, s31, s64
	s_addc_u32 s27, s33, 0
	v_cvt_pk_bf16_f32 v28, v28, v29
	v_cvt_pk_bf16_f32 v29, v30, v31
	v_cvt_pk_bf16_f32 v30, v24, v25
	v_lshl_add_u64 v[24:25], s[26:27], 0, v[184:185]
	s_add_u32 s26, s36, s64
	s_addc_u32 s27, s37, 0
	v_cvt_pk_bf16_f32 v20, v20, v21
	v_cvt_pk_bf16_f32 v21, v22, v23
	v_cvt_pk_bf16_f32 v22, v16, v17
	v_lshl_add_u64 v[16:17], s[26:27], 0, v[184:185]
	s_add_u32 s26, s66, s64
	s_addc_u32 s27, s67, 0
	v_cvt_pk_bf16_f32 v12, v12, v13
	v_cvt_pk_bf16_f32 v13, v14, v15
	v_cvt_pk_bf16_f32 v14, v8, v9
	v_lshl_add_u64 v[8:9], s[26:27], 0, v[184:185]
	s_add_u32 s26, s20, s64
	s_addc_u32 s27, s30, 0
	v_mov_b32_e32 v141, v185
	v_cvt_pk_bf16_f32 v4, v4, v5
	v_cvt_pk_bf16_f32 v5, v6, v7
	v_cvt_pk_bf16_f32 v6, v0, v1
	v_lshl_add_u64 v[0:1], s[26:27], 0, v[184:185]
	v_readlane_b32 s78, v253, 22
	v_readlane_b32 s79, v253, 23
	v_lshl_add_u64 v[120:121], v[120:121], 0, v[140:141]
	v_lshl_add_u64 v[112:113], v[112:113], 0, v[140:141]
	v_lshl_add_u64 v[104:105], v[104:105], 0, v[140:141]
	v_lshl_add_u64 v[96:97], v[96:97], 0, v[140:141]
	v_lshl_add_u64 v[88:89], v[88:89], 0, v[140:141]
	v_lshl_add_u64 v[80:81], v[80:81], 0, v[140:141]
	v_lshl_add_u64 v[72:73], v[72:73], 0, v[140:141]
	v_lshl_add_u64 v[64:65], v[64:65], 0, v[140:141]
	v_lshl_add_u64 v[56:57], v[56:57], 0, v[140:141]
	v_lshl_add_u64 v[48:49], v[48:49], 0, v[140:141]
	v_lshl_add_u64 v[40:41], v[40:41], 0, v[140:141]
	v_lshl_add_u64 v[32:33], v[32:33], 0, v[140:141]
	v_lshl_add_u64 v[24:25], v[24:25], 0, v[140:141]
	v_lshl_add_u64 v[16:17], v[16:17], 0, v[140:141]
	v_lshl_add_u64 v[8:9], v[8:9], 0, v[140:141]
	v_lshl_add_u64 v[0:1], v[0:1], 0, v[140:141]
	s_and_b64 vcc, exec, s[0:1]
	s_mov_b32 s71, s65
	s_mov_b32 s70, s68
	s_mov_b32 s56, s69
	v_readlane_b32 s96, v255, 22
	v_cvt_pk_bf16_f32 v127, v122, v123
	v_readlane_b32 s73, v253, 17
	v_readlane_b32 s76, v253, 20
	v_readlane_b32 s77, v253, 21
	v_readlane_b32 s80, v253, 24
	v_readlane_b32 s81, v253, 25
	v_readlane_b32 s82, v253, 26
	v_readlane_b32 s83, v253, 27
	v_readlane_b32 s84, v253, 28
	v_readlane_b32 s85, v253, 29
	v_readlane_b32 s86, v253, 30
	v_readlane_b32 s87, v253, 31
	global_store_dwordx4 v[120:121], v[124:127], off
	v_cvt_pk_bf16_f32 v119, v114, v115
	global_store_dwordx4 v[112:113], v[116:119], off
	v_cvt_pk_bf16_f32 v111, v106, v107
	global_store_dwordx4 v[104:105], v[108:111], off
	v_cvt_pk_bf16_f32 v103, v98, v99
	global_store_dwordx4 v[96:97], v[100:103], off
	v_cvt_pk_bf16_f32 v95, v90, v91
	global_store_dwordx4 v[88:89], v[92:95], off
	v_cvt_pk_bf16_f32 v87, v82, v83
	global_store_dwordx4 v[80:81], v[84:87], off
	v_cvt_pk_bf16_f32 v79, v74, v75
	global_store_dwordx4 v[72:73], v[76:79], off
	v_cvt_pk_bf16_f32 v71, v66, v67
	global_store_dwordx4 v[64:65], v[68:71], off
	v_cvt_pk_bf16_f32 v63, v58, v59
	global_store_dwordx4 v[56:57], v[60:63], off
	v_cvt_pk_bf16_f32 v55, v50, v51
	global_store_dwordx4 v[48:49], v[52:55], off
	v_cvt_pk_bf16_f32 v47, v42, v43
	global_store_dwordx4 v[40:41], v[44:47], off
	v_cvt_pk_bf16_f32 v39, v34, v35
	global_store_dwordx4 v[32:33], v[36:39], off
	v_cvt_pk_bf16_f32 v31, v26, v27
	global_store_dwordx4 v[24:25], v[28:31], off
	v_cvt_pk_bf16_f32 v23, v18, v19
	global_store_dwordx4 v[16:17], v[20:23], off
	v_cvt_pk_bf16_f32 v15, v10, v11
	global_store_dwordx4 v[8:9], v[12:15], off
	v_cvt_pk_bf16_f32 v7, v2, v3
	global_store_dwordx4 v[0:1], v[4:7], off
	s_cbranch_vccz .LBB0_233
	v_readlane_b32 s84, v255, 43
	s_waitcnt vmcnt(0)
	v_readlane_b32 s86, v255, 45
	v_readlane_b32 s87, v255, 46
	v_readlane_b32 s72, v255, 23
	v_readlane_b32 s86, v255, 31
	s_cmpk_gt_u32 s93, 0xff
	v_readlane_b32 s85, v255, 44
	v_readlane_b32 s73, v255, 24
	v_readlane_b32 s74, v255, 25
	v_readlane_b32 s75, v255, 26
	v_readlane_b32 s76, v255, 27
	v_readlane_b32 s77, v255, 28
	v_readlane_b32 s78, v255, 29
	v_readlane_b32 s79, v255, 30
	s_mov_b32 s80, s57
	v_readlane_b32 s93, v255, 34
	v_readlane_b32 s81, v255, 33
	v_readlane_b32 s87, v255, 32
	s_mov_b32 s70, 0xbfb8aa3b
	s_mov_b32 s71, 0x42ce8ed0
	s_cbranch_scc1 .LBB0_238
	s_barrier

.LBB0_243:
	v_and_b32_e32 v16, 15, v6
	v_and_b32_e32 v17, 48, v6
	v_lshlrev_b32_e32 v6, 2, v6
	s_and_b32 s28, s26, 3
	v_lshl_or_b32 v7, v16, 6, v17
	s_lshl_b32 s26, s20, 13
	v_and_b32_e32 v6, 32, v6
	v_lshl_add_u64 v[8:9], s[22:23], 0, v[184:185]
	v_mov_b32_e32 v129, v185
	v_readlane_b32 s48, v253, 0
	v_bitop3_b32 v142, v7, s26, v6 bitop3:0xde
	s_lshl_b32 s26, s28, 12
	s_add_i32 s45, s38, 0x18000
	v_lshl_add_u64 v[10:11], s[22:23], 0, v[128:129]
	v_mov_b32_e32 v133, v185
	v_readlane_b32 s62, v253, 14
	v_readlane_b32 s63, v253, 15
	v_bitop3_b32 v143, v7, s26, v6 bitop3:0xde
	v_lshl_add_u64 v[6:7], v[8:9], 0, s[24:25]
	s_mov_b32 m0, s45
	s_add_i32 s46, s38, 0x1a000
	v_lshl_add_u64 v[12:13], s[62:63], 0, v[132:133]
	v_mov_b32_e32 v131, v185
	s_waitcnt vmcnt(2)
	s_barrier
	global_load_lds_dwordx4 v[6:7], off
	v_lshl_add_u64 v[6:7], v[10:11], 0, s[24:25]
	s_mov_b32 m0, s46
	s_add_i32 s47, s38, 0x8000
	s_add_i32 s48, s38, 0xa000
	v_readlane_b32 s49, v253, 1
	v_lshl_add_u64 v[14:15], s[62:63], 0, v[130:131]
	global_load_lds_dwordx4 v[6:7], off
	v_lshl_add_u64 v[6:7], v[12:13], 0, s[24:25]
	s_mov_b32 m0, s47
	s_add_u32 s26, s22, 0x100080
	v_readlane_b32 s50, v253, 2
	global_load_lds_dwordx4 v[6:7], off
	v_lshl_add_u64 v[6:7], v[14:15], 0, s[24:25]
	s_mov_b32 m0, s48
	s_addc_u32 s27, s23, 0
	s_add_i32 s49, s38, 0x1c000
	global_load_lds_dwordx4 v[6:7], off
	v_lshl_add_u64 v[6:7], s[26:27], 0, v[184:185]
	s_mov_b32 m0, s49
	s_add_i32 s50, s38, 0x1e000
	global_load_lds_dwordx4 v[6:7], off
	v_lshl_add_u64 v[6:7], s[26:27], 0, v[128:129]
	s_mov_b32 m0, s50
	v_readlane_b32 s51, v253, 3
	global_load_lds_dwordx4 v[6:7], off
	s_lshl_b32 s51, s20, 2
	s_lshl_b32 s20, s28, 10
	v_readlane_b32 s4, v254, 33
	s_add_u32 s26, s4, s20
	v_readlane_b32 s4, v254, 34
	s_addc_u32 s27, s4, 0
	v_lshlrev_b32_e32 v6, 4, v17
	v_mov_b32_e32 v7, v185
	v_lshl_add_u64 v[6:7], s[26:27], 0, v[6:7]
	v_lshlrev_b32_e32 v8, 4, v16
	v_mov_b32_e32 v9, v185
	v_lshl_add_u64 v[134:135], v[6:7], 0, v[8:9]
	v_lshlrev_b32_e32 v6, 13, v4
	v_and_b32_e32 v6, 0xffffc000, v6
	v_lshl_add_u32 v3, v3, 10, v6
	v_and_b32_e32 v4, 1, v4
	v_lshl_or_b32 v3, v4, 6, v3
	v_lshl_add_u32 v138, v5, 1, v3
	v_lshlrev_b32_e32 v3, 13, v0
	v_and_b32_e32 v3, 0xffffc000, v3
	s_waitcnt vmcnt(6)
	v_lshl_add_u32 v1, v1, 10, v3
	v_and_b32_e32 v0, 1, v0
	v_readlane_b32 s52, v253, 4
	v_readlane_b32 s53, v253, 5
	v_readlane_b32 s54, v253, 6
	v_readlane_b32 s55, v253, 7
	v_readlane_b32 s59, v253, 11
	v_lshl_or_b32 v0, v0, 6, v1
	v_readlane_b32 s58, v253, 10
	s_or_b32 s52, s51, 1
	s_or_b32 s53, s51, 2
	s_or_b32 s54, s51, 3
	v_lshl_add_u64 v[136:137], v[134:135], 0, s[94:95]
	v_mov_b32_e32 v139, v185
	v_lshl_add_u32 v140, v2, 1, v0
	v_mov_b32_e32 v141, v185
	s_mov_b32 s55, 0
	s_mov_b32 s59, s0
	v_readlane_b32 s56, v253, 8
	v_readlane_b32 s57, v253, 9
	v_readlane_b32 s60, v253, 12
	v_readlane_b32 s61, v253, 13
	s_barrier
.LBB0_244:
	s_add_i32 s55, s55, 1
	s_mov_b64 s[26:27], s[22:23]
	s_mul_i32 s22, s55, s90
	s_mov_b32 s20, s58
	s_add_i32 s58, s22, s0
	s_cmp_lt_i32 s58, 8
	s_cselect_b32 s22, s58, s20
	s_ashr_i32 s23, s22, 31
	v_readlane_b32 s4, v253, 16
	s_lshl_b64 s[22:23], s[22:23], 10
	v_readlane_b32 s12, v253, 24
	v_readlane_b32 s13, v253, 25
	s_add_u32 s22, s12, s22
	s_addc_u32 s23, s13, s23
	s_cmp_lt_i32 s58, 8
	s_cselect_b32 s20, s23, s27
	s_cselect_b32 s60, s22, s26
	s_cmp_gt_i32 s58, 7
	s_cselect_b64 s[28:29], -1, 0
	s_add_u32 s26, s26, 0x100
	v_mov_b32_e32 v0, 0
	v_readlane_b32 s30, v255, 17
	v_readlane_b32 s64, v253, 0
	s_addc_u32 s27, s27, 0
	s_mov_b32 s61, -2
	v_readlane_b32 s31, v255, 18
	v_mov_b32_e32 v1, v0
	v_mov_b32_e32 v2, v0
	v_mov_b32_e32 v3, v0
	v_mov_b32_e32 v4, v0
	v_mov_b32_e32 v5, v0
	v_mov_b32_e32 v6, v0
	v_mov_b32_e32 v7, v0
	v_mov_b32_e32 v8, v0
	v_mov_b32_e32 v9, v0
	v_mov_b32_e32 v10, v0
	v_mov_b32_e32 v11, v0
	v_mov_b32_e32 v12, v0
	v_mov_b32_e32 v13, v0
	v_mov_b32_e32 v14, v0
	v_mov_b32_e32 v15, v0
	v_mov_b32_e32 v16, v0
	v_mov_b32_e32 v17, v0
	v_mov_b32_e32 v18, v0
	v_mov_b32_e32 v19, v0
	v_mov_b32_e32 v20, v0
	v_mov_b32_e32 v21, v0
	v_mov_b32_e32 v22, v0
	v_mov_b32_e32 v23, v0
	v_mov_b32_e32 v24, v0
	v_mov_b32_e32 v25, v0
	v_mov_b32_e32 v26, v0
	v_mov_b32_e32 v27, v0
	v_mov_b32_e32 v28, v0
	v_mov_b32_e32 v29, v0
	v_mov_b32_e32 v30, v0
	v_mov_b32_e32 v31, v0
	v_mov_b32_e32 v32, v0
	v_mov_b32_e32 v33, v0
	v_mov_b32_e32 v34, v0
	v_mov_b32_e32 v35, v0
	v_mov_b32_e32 v36, v0
	v_mov_b32_e32 v37, v0
	v_mov_b32_e32 v38, v0
	v_mov_b32_e32 v39, v0
	v_mov_b32_e32 v40, v0
	v_mov_b32_e32 v41, v0
	v_mov_b32_e32 v42, v0
	v_mov_b32_e32 v43, v0
	v_mov_b32_e32 v44, v0
	v_mov_b32_e32 v45, v0
	v_mov_b32_e32 v46, v0
	v_mov_b32_e32 v47, v0
	v_mov_b32_e32 v48, v0
	v_mov_b32_e32 v49, v0
	v_mov_b32_e32 v50, v0
	v_mov_b32_e32 v51, v0
	v_mov_b32_e32 v52, v0
	v_mov_b32_e32 v53, v0
	v_mov_b32_e32 v54, v0
	v_mov_b32_e32 v55, v0
	v_mov_b32_e32 v56, v0
	v_mov_b32_e32 v57, v0
	v_mov_b32_e32 v58, v0
	v_mov_b32_e32 v59, v0
	v_mov_b32_e32 v60, v0
	v_mov_b32_e32 v61, v0
	v_mov_b32_e32 v62, v0
	v_mov_b32_e32 v63, v0
	v_mov_b32_e32 v64, v0
	v_mov_b32_e32 v65, v0
	v_mov_b32_e32 v66, v0
	v_mov_b32_e32 v67, v0
	v_mov_b32_e32 v68, v0
	v_mov_b32_e32 v69, v0
	v_mov_b32_e32 v70, v0
	v_mov_b32_e32 v71, v0
	v_mov_b32_e32 v72, v0
	v_mov_b32_e32 v73, v0
	v_mov_b32_e32 v74, v0
	v_mov_b32_e32 v75, v0
	v_mov_b32_e32 v76, v0
	v_mov_b32_e32 v77, v0
	v_mov_b32_e32 v78, v0
	v_mov_b32_e32 v79, v0
	v_mov_b32_e32 v80, v0
	v_mov_b32_e32 v81, v0
	v_mov_b32_e32 v82, v0
	v_mov_b32_e32 v83, v0
	v_mov_b32_e32 v84, v0
	v_mov_b32_e32 v85, v0
	v_mov_b32_e32 v86, v0
	v_mov_b32_e32 v87, v0
	v_mov_b32_e32 v88, v0
	v_mov_b32_e32 v89, v0
	v_mov_b32_e32 v90, v0
	v_mov_b32_e32 v91, v0
	v_mov_b32_e32 v92, v0
	v_mov_b32_e32 v93, v0
	v_mov_b32_e32 v94, v0
	v_mov_b32_e32 v95, v0
	v_mov_b32_e32 v96, v0
	v_mov_b32_e32 v97, v0
	v_mov_b32_e32 v98, v0
	v_mov_b32_e32 v99, v0
	v_mov_b32_e32 v100, v0
	v_mov_b32_e32 v101, v0
	v_mov_b32_e32 v102, v0
	v_mov_b32_e32 v103, v0
	v_mov_b32_e32 v104, v0
	v_mov_b32_e32 v105, v0
	v_mov_b32_e32 v106, v0
	v_mov_b32_e32 v107, v0
	v_mov_b32_e32 v108, v0
	v_mov_b32_e32 v109, v0
	v_mov_b32_e32 v110, v0
	v_mov_b32_e32 v111, v0
	v_mov_b32_e32 v112, v0
	v_mov_b32_e32 v113, v0
	v_mov_b32_e32 v114, v0
	v_mov_b32_e32 v115, v0
	v_mov_b32_e32 v116, v0
	v_mov_b32_e32 v117, v0
	v_mov_b32_e32 v118, v0
	v_mov_b32_e32 v119, v0
	v_mov_b32_e32 v120, v0
	v_mov_b32_e32 v121, v0
	v_mov_b32_e32 v122, v0
	v_mov_b32_e32 v123, v0
	v_mov_b32_e32 v124, v0
	v_mov_b32_e32 v125, v0
	v_mov_b32_e32 v126, v0
	v_mov_b32_e32 v127, v0
	v_readlane_b32 s78, v253, 14
	v_readlane_b32 s79, v253, 15
	v_readlane_b32 s5, v253, 17
	v_readlane_b32 s6, v253, 18
	v_readlane_b32 s7, v253, 19
	v_readlane_b32 s8, v253, 20
	v_readlane_b32 s9, v253, 21
	v_readlane_b32 s10, v253, 22
	v_readlane_b32 s11, v253, 23
	v_readlane_b32 s14, v253, 26
	v_readlane_b32 s15, v253, 27
	v_readlane_b32 s16, v253, 28
	v_readlane_b32 s17, v253, 29
	v_readlane_b32 s18, v253, 30
	v_readlane_b32 s19, v253, 31
	v_readlane_b32 s65, v253, 1
	v_readlane_b32 s66, v253, 2
	v_readlane_b32 s67, v253, 3
	v_readlane_b32 s68, v253, 4
	v_readlane_b32 s69, v253, 5
	v_readlane_b32 s70, v253, 6
	v_readlane_b32 s71, v253, 7
	v_readlane_b32 s72, v253, 8
	v_readlane_b32 s73, v253, 9
	v_readlane_b32 s74, v253, 10
	v_readlane_b32 s75, v253, 11
	v_readlane_b32 s76, v253, 12
	v_readlane_b32 s77, v253, 13
	v_add_u32_e32 v230, 0x10000, v143
.LBB0_245:
	ds_read_b128 v[144:147], v230
	ds_read_b128 v[148:151], v230 offset:1024
	ds_read_b128 v[152:155], v230 offset:2048
	ds_read_b128 v[156:159], v230 offset:3072
	s_add_u32 s34, s30, 0xfffe0080
	s_addc_u32 s35, s31, -1
	s_cmp_eq_u32 s61, 4
	s_cselect_b32 s37, s79, s35
	s_cselect_b32 s36, s78, s34
	s_cselect_b32 s35, s20, s27
	s_cselect_b32 s34, s60, s26
	v_lshl_add_u64 v[190:191], s[30:31], 0, v[138:139]
	s_add_i32 m0, s38, 0xc000
	ds_read_b128 v[160:163], v142
	ds_read_b128 v[164:167], v142 offset:1024
	ds_read_b128 v[168:171], v142 offset:2048
	ds_read_b128 v[172:175], v142 offset:3072
	ds_read_b128 v[176:179], v142 offset:4096
	ds_read_b128 v[180:183], v142 offset:5120
	ds_read_b128 v[186:189], v142 offset:6144
	ds_read_b128 v[194:197], v142 offset:7168
	global_load_lds_dwordx4 v[190:191], off
	v_lshl_add_u64 v[190:191], s[30:31], 0, v[140:141]
	s_add_i32 m0, s38, 0xe000
	s_nop 0
	global_load_lds_dwordx4 v[190:191], off
	ds_read_b128 v[198:201], v230 offset:16384
	ds_read_b128 v[202:205], v230 offset:17408
	ds_read_b128 v[206:209], v230 offset:18432
	ds_read_b128 v[210:213], v230 offset:19456
	s_waitcnt vmcnt(8) lgkmcnt(0)
	s_barrier
	v_mfma_f32_16x16x32_bf16 v[124:127], v[144:147], v[160:163], v[124:127]
	v_mfma_f32_16x16x32_bf16 v[120:123], v[152:155], v[160:163], v[120:123]
	v_mfma_f32_16x16x32_bf16 v[116:119], v[144:147], v[168:171], v[116:119]
	v_mfma_f32_16x16x32_bf16 v[112:115], v[152:155], v[168:171], v[112:115]
	v_mfma_f32_16x16x32_bf16 v[108:111], v[144:147], v[176:179], v[108:111]
	v_mfma_f32_16x16x32_bf16 v[104:107], v[152:155], v[176:179], v[104:107]
	v_mfma_f32_16x16x32_bf16 v[100:103], v[144:147], v[186:189], v[100:103]
	v_mfma_f32_16x16x32_bf16 v[96:99], v[152:155], v[186:189], v[96:99]
	v_mfma_f32_16x16x32_bf16 v[124:127], v[148:151], v[164:167], v[124:127]
	v_mfma_f32_16x16x32_bf16 v[120:123], v[156:159], v[164:167], v[120:123]
	v_mfma_f32_16x16x32_bf16 v[116:119], v[148:151], v[172:175], v[116:119]
	v_mfma_f32_16x16x32_bf16 v[112:115], v[156:159], v[172:175], v[112:115]
	v_mfma_f32_16x16x32_bf16 v[108:111], v[148:151], v[180:183], v[108:111]
	v_mfma_f32_16x16x32_bf16 v[104:107], v[156:159], v[180:183], v[104:107]
	v_mfma_f32_16x16x32_bf16 v[100:103], v[148:151], v[194:197], v[100:103]
	v_mfma_f32_16x16x32_bf16 v[96:99], v[156:159], v[194:197], v[96:99]
	v_mfma_f32_16x16x32_bf16 v[92:95], v[198:201], v[160:163], v[92:95]
	v_mfma_f32_16x16x32_bf16 v[88:91], v[206:209], v[160:163], v[88:91]
	v_mfma_f32_16x16x32_bf16 v[84:87], v[198:201], v[168:171], v[84:87]
	v_mfma_f32_16x16x32_bf16 v[80:83], v[206:209], v[168:171], v[80:83]
	v_mfma_f32_16x16x32_bf16 v[76:79], v[198:201], v[176:179], v[76:79]
	v_mfma_f32_16x16x32_bf16 v[72:75], v[206:209], v[176:179], v[72:75]
	v_mfma_f32_16x16x32_bf16 v[68:71], v[198:201], v[186:189], v[68:71]
	v_mfma_f32_16x16x32_bf16 v[64:67], v[206:209], v[186:189], v[64:67]
	v_mfma_f32_16x16x32_bf16 v[92:95], v[202:205], v[164:167], v[92:95]
	v_mfma_f32_16x16x32_bf16 v[88:91], v[210:213], v[164:167], v[88:91]
	v_mfma_f32_16x16x32_bf16 v[84:87], v[202:205], v[172:175], v[84:87]
	v_mfma_f32_16x16x32_bf16 v[80:83], v[210:213], v[172:175], v[80:83]
	v_mfma_f32_16x16x32_bf16 v[76:79], v[202:205], v[180:183], v[76:79]
	v_mfma_f32_16x16x32_bf16 v[72:75], v[210:213], v[180:183], v[72:75]
	v_mfma_f32_16x16x32_bf16 v[68:71], v[202:205], v[194:197], v[68:71]
	v_mfma_f32_16x16x32_bf16 v[64:67], v[210:213], v[194:197], v[64:67]
	s_barrier
	s_mov_b32 m0, s1
	v_lshl_add_u64 v[190:191], s[34:35], 0, v[184:185]
	global_load_lds_dwordx4 v[190:191], off
	v_lshl_add_u64 v[214:215], s[34:35], 0, v[128:129]
	s_mov_b32 m0, s39
	s_nop 0
	global_load_lds_dwordx4 v[214:215], off
	s_mov_b32 m0, s38
	v_lshl_add_u64 v[216:217], s[36:37], 0, v[132:133]
	ds_read_b128 v[160:163], v142 offset:16384
	ds_read_b128 v[164:167], v142 offset:17408
	ds_read_b128 v[168:171], v142 offset:18432
	ds_read_b128 v[172:175], v142 offset:19456
	ds_read_b128 v[176:179], v142 offset:20480
	ds_read_b128 v[180:183], v142 offset:21504
	ds_read_b128 v[186:189], v142 offset:22528
	ds_read_b128 v[194:197], v142 offset:23552
	global_load_lds_dwordx4 v[216:217], off
	v_lshl_add_u64 v[242:243], s[36:37], 0, v[130:131]
	s_mov_b32 m0, s40
	s_nop 0
	global_load_lds_dwordx4 v[242:243], off
	s_waitcnt vmcnt(6) lgkmcnt(0)
	s_barrier
	v_mfma_f32_16x16x32_bf16 v[60:63], v[144:147], v[160:163], v[60:63]
	v_mfma_f32_16x16x32_bf16 v[56:59], v[152:155], v[160:163], v[56:59]
	v_mfma_f32_16x16x32_bf16 v[52:55], v[144:147], v[168:171], v[52:55]
	v_mfma_f32_16x16x32_bf16 v[48:51], v[152:155], v[168:171], v[48:51]
	v_mfma_f32_16x16x32_bf16 v[44:47], v[144:147], v[176:179], v[44:47]
	v_mfma_f32_16x16x32_bf16 v[40:43], v[152:155], v[176:179], v[40:43]
	v_mfma_f32_16x16x32_bf16 v[36:39], v[144:147], v[186:189], v[36:39]
	v_mfma_f32_16x16x32_bf16 v[32:35], v[152:155], v[186:189], v[32:35]
	v_mfma_f32_16x16x32_bf16 v[60:63], v[148:151], v[164:167], v[60:63]
	v_mfma_f32_16x16x32_bf16 v[56:59], v[156:159], v[164:167], v[56:59]
	v_mfma_f32_16x16x32_bf16 v[52:55], v[148:151], v[172:175], v[52:55]
	v_mfma_f32_16x16x32_bf16 v[48:51], v[156:159], v[172:175], v[48:51]
	v_mfma_f32_16x16x32_bf16 v[44:47], v[148:151], v[180:183], v[44:47]
	v_mfma_f32_16x16x32_bf16 v[40:43], v[156:159], v[180:183], v[40:43]
	v_mfma_f32_16x16x32_bf16 v[36:39], v[148:151], v[194:197], v[36:39]
	v_mfma_f32_16x16x32_bf16 v[32:35], v[156:159], v[194:197], v[32:35]
	v_mfma_f32_16x16x32_bf16 v[28:31], v[198:201], v[160:163], v[28:31]
	v_mfma_f32_16x16x32_bf16 v[24:27], v[206:209], v[160:163], v[24:27]
	v_mfma_f32_16x16x32_bf16 v[20:23], v[198:201], v[168:171], v[20:23]
	v_mfma_f32_16x16x32_bf16 v[16:19], v[206:209], v[168:171], v[16:19]
	v_mfma_f32_16x16x32_bf16 v[12:15], v[198:201], v[176:179], v[12:15]
	v_mfma_f32_16x16x32_bf16 v[8:11], v[206:209], v[176:179], v[8:11]
	v_mfma_f32_16x16x32_bf16 v[4:7], v[198:201], v[186:189], v[4:7]
	v_mfma_f32_16x16x32_bf16 v[0:3], v[206:209], v[186:189], v[0:3]
	v_mfma_f32_16x16x32_bf16 v[28:31], v[202:205], v[164:167], v[28:31]
	v_mfma_f32_16x16x32_bf16 v[24:27], v[210:213], v[164:167], v[24:27]
	v_mfma_f32_16x16x32_bf16 v[20:23], v[202:205], v[172:175], v[20:23]
	v_mfma_f32_16x16x32_bf16 v[16:19], v[210:213], v[172:175], v[16:19]
	v_mfma_f32_16x16x32_bf16 v[12:15], v[202:205], v[180:183], v[12:15]
	v_mfma_f32_16x16x32_bf16 v[8:11], v[210:213], v[180:183], v[8:11]
	v_mfma_f32_16x16x32_bf16 v[4:7], v[202:205], v[194:197], v[4:7]
	v_mfma_f32_16x16x32_bf16 v[0:3], v[210:213], v[194:197], v[0:3]
	s_barrier
	s_add_u32 s62, s34, 0x100000
	s_addc_u32 s63, s35, 0
	s_mov_b32 m0, s41
	v_lshl_add_u64 v[144:145], s[62:63], 0, v[184:185]
	global_load_lds_dwordx4 v[144:145], off
	v_lshl_add_u64 v[144:145], s[62:63], 0, v[128:129]
	s_mov_b32 m0, s42
	s_nop 0
	global_load_lds_dwordx4 v[144:145], off
	ds_read_b128 v[144:147], v230 offset:32768
	ds_read_b128 v[148:151], v230 offset:33792
	ds_read_b128 v[152:155], v230 offset:34816
	ds_read_b128 v[156:159], v230 offset:35840
	s_add_u32 s36, s36, 0x20000
	s_addc_u32 s37, s37, 0
	s_mov_b32 m0, s43
	v_lshl_add_u64 v[198:199], s[36:37], 0, v[132:133]
	ds_read_b128 v[160:163], v142 offset:32768
	ds_read_b128 v[164:167], v142 offset:33792
	ds_read_b128 v[168:171], v142 offset:34816
	ds_read_b128 v[172:175], v142 offset:35840
	ds_read_b128 v[176:179], v142 offset:36864
	ds_read_b128 v[180:183], v142 offset:37888
	ds_read_b128 v[186:189], v142 offset:38912
	ds_read_b128 v[194:197], v142 offset:39936
	global_load_lds_dwordx4 v[198:199], off
	v_lshl_add_u64 v[198:199], s[36:37], 0, v[130:131]
	s_mov_b32 m0, s44
	s_nop 0
	global_load_lds_dwordx4 v[198:199], off
	ds_read_b128 v[198:201], v230 offset:49152
	ds_read_b128 v[202:205], v230 offset:50176
	ds_read_b128 v[206:209], v230 offset:51200
	ds_read_b128 v[210:213], v230 offset:52224
	s_waitcnt vmcnt(8) lgkmcnt(0)
	s_barrier
	v_mfma_f32_16x16x32_bf16 v[124:127], v[144:147], v[160:163], v[124:127]
	v_mfma_f32_16x16x32_bf16 v[120:123], v[152:155], v[160:163], v[120:123]
	v_mfma_f32_16x16x32_bf16 v[116:119], v[144:147], v[168:171], v[116:119]
	v_mfma_f32_16x16x32_bf16 v[112:115], v[152:155], v[168:171], v[112:115]
	v_mfma_f32_16x16x32_bf16 v[108:111], v[144:147], v[176:179], v[108:111]
	v_mfma_f32_16x16x32_bf16 v[104:107], v[152:155], v[176:179], v[104:107]
	v_mfma_f32_16x16x32_bf16 v[100:103], v[144:147], v[186:189], v[100:103]
	v_mfma_f32_16x16x32_bf16 v[96:99], v[152:155], v[186:189], v[96:99]
	v_mfma_f32_16x16x32_bf16 v[124:127], v[148:151], v[164:167], v[124:127]
	v_mfma_f32_16x16x32_bf16 v[120:123], v[156:159], v[164:167], v[120:123]
	v_mfma_f32_16x16x32_bf16 v[116:119], v[148:151], v[172:175], v[116:119]
	v_mfma_f32_16x16x32_bf16 v[112:115], v[156:159], v[172:175], v[112:115]
	v_mfma_f32_16x16x32_bf16 v[108:111], v[148:151], v[180:183], v[108:111]
	v_mfma_f32_16x16x32_bf16 v[104:107], v[156:159], v[180:183], v[104:107]
	v_mfma_f32_16x16x32_bf16 v[100:103], v[148:151], v[194:197], v[100:103]
	v_mfma_f32_16x16x32_bf16 v[96:99], v[156:159], v[194:197], v[96:99]
	v_mfma_f32_16x16x32_bf16 v[92:95], v[198:201], v[160:163], v[92:95]
	v_mfma_f32_16x16x32_bf16 v[88:91], v[206:209], v[160:163], v[88:91]
	v_mfma_f32_16x16x32_bf16 v[84:87], v[198:201], v[168:171], v[84:87]
	v_mfma_f32_16x16x32_bf16 v[80:83], v[206:209], v[168:171], v[80:83]
	v_mfma_f32_16x16x32_bf16 v[76:79], v[198:201], v[176:179], v[76:79]
	v_mfma_f32_16x16x32_bf16 v[72:75], v[206:209], v[176:179], v[72:75]
	v_mfma_f32_16x16x32_bf16 v[68:71], v[198:201], v[186:189], v[68:71]
	v_mfma_f32_16x16x32_bf16 v[64:67], v[206:209], v[186:189], v[64:67]
	v_mfma_f32_16x16x32_bf16 v[92:95], v[202:205], v[164:167], v[92:95]
	v_mfma_f32_16x16x32_bf16 v[88:91], v[210:213], v[164:167], v[88:91]
	v_mfma_f32_16x16x32_bf16 v[84:87], v[202:205], v[172:175], v[84:87]
	v_mfma_f32_16x16x32_bf16 v[80:83], v[210:213], v[172:175], v[80:83]
	v_mfma_f32_16x16x32_bf16 v[76:79], v[202:205], v[180:183], v[76:79]
	v_mfma_f32_16x16x32_bf16 v[72:75], v[210:213], v[180:183], v[72:75]
	v_mfma_f32_16x16x32_bf16 v[68:71], v[202:205], v[194:197], v[68:71]
	v_mfma_f32_16x16x32_bf16 v[64:67], v[210:213], v[194:197], v[64:67]
	s_barrier
	s_mov_b32 m0, s45
	v_lshl_add_u64 v[190:191], v[190:191], 0, s[24:25]
	global_load_lds_dwordx4 v[190:191], off
	v_lshl_add_u64 v[190:191], v[214:215], 0, s[24:25]
	s_mov_b32 m0, s46
	s_nop 0
	global_load_lds_dwordx4 v[190:191], off
	s_mov_b32 m0, s47
	v_lshl_add_u64 v[190:191], v[216:217], 0, s[24:25]
	ds_read_b128 v[160:163], v142 offset:49152
	ds_read_b128 v[164:167], v142 offset:50176
	ds_read_b128 v[168:171], v142 offset:51200
	ds_read_b128 v[172:175], v142 offset:52224
	ds_read_b128 v[176:179], v142 offset:53248
	ds_read_b128 v[180:183], v142 offset:54272
	ds_read_b128 v[186:189], v142 offset:55296
	ds_read_b128 v[194:197], v142 offset:56320
	global_load_lds_dwordx4 v[190:191], off
	v_lshl_add_u64 v[190:191], v[242:243], 0, s[24:25]
	s_mov_b32 m0, s48
	s_nop 0
	global_load_lds_dwordx4 v[190:191], off
	s_waitcnt vmcnt(6) lgkmcnt(0)
	s_barrier
	v_mfma_f32_16x16x32_bf16 v[60:63], v[144:147], v[160:163], v[60:63]
	v_mfma_f32_16x16x32_bf16 v[56:59], v[152:155], v[160:163], v[56:59]
	v_mfma_f32_16x16x32_bf16 v[52:55], v[144:147], v[168:171], v[52:55]
	v_mfma_f32_16x16x32_bf16 v[48:51], v[152:155], v[168:171], v[48:51]
	v_mfma_f32_16x16x32_bf16 v[44:47], v[144:147], v[176:179], v[44:47]
	v_mfma_f32_16x16x32_bf16 v[40:43], v[152:155], v[176:179], v[40:43]
	v_mfma_f32_16x16x32_bf16 v[36:39], v[144:147], v[186:189], v[36:39]
	v_mfma_f32_16x16x32_bf16 v[32:35], v[152:155], v[186:189], v[32:35]
	v_mfma_f32_16x16x32_bf16 v[60:63], v[148:151], v[164:167], v[60:63]
	v_mfma_f32_16x16x32_bf16 v[56:59], v[156:159], v[164:167], v[56:59]
	v_mfma_f32_16x16x32_bf16 v[52:55], v[148:151], v[172:175], v[52:55]
	v_mfma_f32_16x16x32_bf16 v[48:51], v[156:159], v[172:175], v[48:51]
	v_mfma_f32_16x16x32_bf16 v[44:47], v[148:151], v[180:183], v[44:47]
	v_mfma_f32_16x16x32_bf16 v[40:43], v[156:159], v[180:183], v[40:43]
	v_mfma_f32_16x16x32_bf16 v[36:39], v[148:151], v[194:197], v[36:39]
	v_mfma_f32_16x16x32_bf16 v[32:35], v[156:159], v[194:197], v[32:35]
	v_mfma_f32_16x16x32_bf16 v[28:31], v[198:201], v[160:163], v[28:31]
	v_mfma_f32_16x16x32_bf16 v[24:27], v[206:209], v[160:163], v[24:27]
	v_mfma_f32_16x16x32_bf16 v[20:23], v[198:201], v[168:171], v[20:23]
	v_mfma_f32_16x16x32_bf16 v[16:19], v[206:209], v[168:171], v[16:19]
	v_mfma_f32_16x16x32_bf16 v[12:15], v[198:201], v[176:179], v[12:15]
	v_mfma_f32_16x16x32_bf16 v[8:11], v[206:209], v[176:179], v[8:11]
	v_mfma_f32_16x16x32_bf16 v[4:7], v[198:201], v[186:189], v[4:7]
	v_mfma_f32_16x16x32_bf16 v[0:3], v[206:209], v[186:189], v[0:3]
	v_mfma_f32_16x16x32_bf16 v[28:31], v[202:205], v[164:167], v[28:31]
	v_mfma_f32_16x16x32_bf16 v[24:27], v[210:213], v[164:167], v[24:27]
	v_mfma_f32_16x16x32_bf16 v[20:23], v[202:205], v[172:175], v[20:23]
	v_mfma_f32_16x16x32_bf16 v[16:19], v[210:213], v[172:175], v[16:19]
	v_mfma_f32_16x16x32_bf16 v[12:15], v[202:205], v[180:183], v[12:15]
	v_mfma_f32_16x16x32_bf16 v[8:11], v[210:213], v[180:183], v[8:11]
	v_mfma_f32_16x16x32_bf16 v[4:7], v[202:205], v[194:197], v[4:7]
	v_mfma_f32_16x16x32_bf16 v[0:3], v[210:213], v[194:197], v[0:3]
	s_barrier
	s_add_u32 s34, s34, 0x100080
	s_addc_u32 s35, s35, 0
	s_mov_b32 m0, s49
	v_lshl_add_u64 v[144:145], s[34:35], 0, v[184:185]
	global_load_lds_dwordx4 v[144:145], off
	v_lshl_add_u64 v[144:145], s[34:35], 0, v[128:129]
	s_mov_b32 m0, s50
	s_nop 0
	global_load_lds_dwordx4 v[144:145], off
	s_add_i32 s61, s61, 2
	s_add_u32 s30, s30, 0x100
	s_addc_u32 s31, s31, 0
	s_add_u32 s26, s26, 0x100
	s_addc_u32 s27, s27, 0
	s_cmp_gt_u32 s61, 5
	s_cbranch_scc0 .LBB0_245
	s_lshl_b32 s20, s59, 4
	s_add_i32 s30, s20, s51
	s_add_i32 s34, s52, s20
	s_add_i32 s36, s53, s20
	s_ashr_i32 s31, s30, 31
	s_ashr_i32 s35, s34, 31
	s_ashr_i32 s37, s36, 31
	s_lshl_b64 s[26:27], s[30:31], 13
	s_lshl_b64 s[34:35], s[34:35], 13
	s_lshl_b64 s[36:37], s[36:37], 13
	v_cvt_pk_bf16_f32 v124, v124, v125
	v_cvt_pk_bf16_f32 v125, v126, v127
	v_cvt_pk_bf16_f32 v126, v120, v121
	v_lshl_add_u64 v[120:121], v[134:135], 0, s[26:27]
	v_cvt_pk_bf16_f32 v116, v116, v117
	v_cvt_pk_bf16_f32 v117, v118, v119
	v_cvt_pk_bf16_f32 v118, v112, v113
	v_lshl_add_u64 v[112:113], v[134:135], 0, s[34:35]
	v_cvt_pk_bf16_f32 v108, v108, v109
	v_cvt_pk_bf16_f32 v109, v110, v111
	v_cvt_pk_bf16_f32 v110, v104, v105
	v_lshl_add_u64 v[104:105], v[134:135], 0, s[36:37]
	s_add_i32 s60, s54, s20
	v_cvt_pk_bf16_f32 v92, v92, v93
	v_cvt_pk_bf16_f32 v93, v94, v95
	v_cvt_pk_bf16_f32 v94, v88, v89
	v_lshl_add_u64 v[88:89], v[136:137], 0, s[26:27]
	v_cvt_pk_bf16_f32 v84, v84, v85
	v_cvt_pk_bf16_f32 v85, v86, v87
	v_cvt_pk_bf16_f32 v86, v80, v81
	v_lshl_add_u64 v[80:81], v[136:137], 0, s[34:35]
	v_cvt_pk_bf16_f32 v76, v76, v77
	v_cvt_pk_bf16_f32 v77, v78, v79
	v_cvt_pk_bf16_f32 v78, v72, v73
	v_lshl_add_u64 v[72:73], v[136:137], 0, s[36:37]
	s_add_i32 s26, s30, 8
	s_add_i32 s34, s30, 9
	s_add_i32 s36, s30, 10
	s_add_i32 s30, s30, 11
	s_ashr_i32 s61, s60, 31
	s_ashr_i32 s27, s26, 31
	s_ashr_i32 s35, s34, 31
	s_ashr_i32 s37, s36, 31
	s_ashr_i32 s31, s30, 31
	s_lshl_b64 s[60:61], s[60:61], 13
	s_lshl_b64 s[26:27], s[26:27], 13
	s_lshl_b64 s[34:35], s[34:35], 13
	s_lshl_b64 s[36:37], s[36:37], 13
	s_lshl_b64 s[30:31], s[30:31], 13
	v_cvt_pk_bf16_f32 v100, v100, v101
	v_cvt_pk_bf16_f32 v101, v102, v103
	v_cvt_pk_bf16_f32 v102, v96, v97
	v_lshl_add_u64 v[96:97], v[134:135], 0, s[60:61]
	v_cvt_pk_bf16_f32 v68, v68, v69
	v_cvt_pk_bf16_f32 v69, v70, v71
	v_cvt_pk_bf16_f32 v70, v64, v65
	v_lshl_add_u64 v[64:65], v[136:137], 0, s[60:61]
	v_cvt_pk_bf16_f32 v60, v60, v61
	v_cvt_pk_bf16_f32 v61, v62, v63
	v_cvt_pk_bf16_f32 v62, v56, v57
	v_lshl_add_u64 v[56:57], v[134:135], 0, s[26:27]
	v_cvt_pk_bf16_f32 v52, v52, v53
	v_cvt_pk_bf16_f32 v53, v54, v55
	v_cvt_pk_bf16_f32 v54, v48, v49
	v_lshl_add_u64 v[48:49], v[134:135], 0, s[34:35]
	v_cvt_pk_bf16_f32 v44, v44, v45
	v_cvt_pk_bf16_f32 v45, v46, v47
	v_cvt_pk_bf16_f32 v46, v40, v41
	v_lshl_add_u64 v[40:41], v[134:135], 0, s[36:37]
	v_cvt_pk_bf16_f32 v36, v36, v37
	v_cvt_pk_bf16_f32 v37, v38, v39
	v_cvt_pk_bf16_f32 v38, v32, v33
	v_lshl_add_u64 v[32:33], v[134:135], 0, s[30:31]
	v_cvt_pk_bf16_f32 v28, v28, v29
	v_cvt_pk_bf16_f32 v29, v30, v31
	v_cvt_pk_bf16_f32 v30, v24, v25
	v_lshl_add_u64 v[24:25], v[136:137], 0, s[26:27]
	v_cvt_pk_bf16_f32 v20, v20, v21
	v_cvt_pk_bf16_f32 v21, v22, v23
	v_cvt_pk_bf16_f32 v22, v16, v17
	v_lshl_add_u64 v[16:17], v[136:137], 0, s[34:35]
	v_cvt_pk_bf16_f32 v12, v12, v13
	v_cvt_pk_bf16_f32 v13, v14, v15
	v_cvt_pk_bf16_f32 v14, v8, v9
	v_lshl_add_u64 v[8:9], v[136:137], 0, s[36:37]
	v_cvt_pk_bf16_f32 v4, v4, v5
	v_cvt_pk_bf16_f32 v5, v6, v7
	v_cvt_pk_bf16_f32 v6, v0, v1
	v_lshl_add_u64 v[0:1], v[136:137], 0, s[30:31]
	s_and_b64 vcc, exec, s[28:29]
	s_mov_b32 s59, s58
	v_cvt_pk_bf16_f32 v127, v122, v123
	global_store_dwordx4 v[120:121], v[124:127], off
	v_cvt_pk_bf16_f32 v119, v114, v115
	global_store_dwordx4 v[112:113], v[116:119], off
	v_cvt_pk_bf16_f32 v111, v106, v107
	global_store_dwordx4 v[104:105], v[108:111], off
	v_cvt_pk_bf16_f32 v103, v98, v99
	global_store_dwordx4 v[96:97], v[100:103], off
	v_cvt_pk_bf16_f32 v95, v90, v91
	global_store_dwordx4 v[88:89], v[92:95], off
	v_cvt_pk_bf16_f32 v87, v82, v83
	global_store_dwordx4 v[80:81], v[84:87], off
	v_cvt_pk_bf16_f32 v79, v74, v75
	global_store_dwordx4 v[72:73], v[76:79], off
	v_cvt_pk_bf16_f32 v71, v66, v67
	global_store_dwordx4 v[64:65], v[68:71], off
	v_cvt_pk_bf16_f32 v63, v58, v59
	global_store_dwordx4 v[56:57], v[60:63], off
	v_cvt_pk_bf16_f32 v55, v50, v51
	global_store_dwordx4 v[48:49], v[52:55], off
	v_cvt_pk_bf16_f32 v47, v42, v43
	global_store_dwordx4 v[40:41], v[44:47], off
	v_cvt_pk_bf16_f32 v39, v34, v35
	global_store_dwordx4 v[32:33], v[36:39], off
	v_cvt_pk_bf16_f32 v31, v26, v27
	global_store_dwordx4 v[24:25], v[28:31], off
	v_cvt_pk_bf16_f32 v23, v18, v19
	global_store_dwordx4 v[16:17], v[20:23], off
	v_cvt_pk_bf16_f32 v15, v10, v11
	global_store_dwordx4 v[8:9], v[12:15], off
	v_cvt_pk_bf16_f32 v7, v2, v3
	global_store_dwordx4 v[0:1], v[4:7], off
	s_cbranch_vccz .LBB0_244
	s_waitcnt vmcnt(0)
	s_cmpk_gt_u32 s33, 0xff
	s_cbranch_scc1 .LBB0_249
	s_barrier

.LBB0_287:
	v_mov_b32_e32 v135, v185
	v_lshl_add_u64 v[8:9], s[28:29], 0, v[134:135]
	v_mov_b32_e32 v139, v185
	s_add_i32 s68, s58, 0x18000
	v_lshl_add_u64 v[10:11], s[28:29], 0, v[138:139]
	v_mov_b32_e32 v133, v185
	s_and_b32 s49, s20, 3
	v_lshl_add_u64 v[8:9], v[8:9], 0, s[24:25]
	s_mov_b32 m0, s68
	s_add_i32 s69, s58, 0x1a000
	v_lshl_add_u64 v[12:13], s[0:1], 0, v[132:133]
	v_mov_b32_e32 v137, v185
	s_lshl_b32 s66, s22, 6
	s_lshl_b32 s20, s22, 13
	s_lshl_b32 s23, s49, 12
	s_waitcnt vmcnt(2)
	s_barrier
	global_load_lds_dwordx4 v[8:9], off
	v_lshl_add_u64 v[8:9], v[10:11], 0, s[24:25]
	s_mov_b32 m0, s69
	s_add_i32 s70, s58, 0x8000
	s_add_i32 s71, s58, 0xa000
	v_lshl_add_u64 v[14:15], s[0:1], 0, v[136:137]
	global_load_lds_dwordx4 v[8:9], off
	v_lshl_add_u64 v[8:9], v[12:13], 0, s[24:25]
	s_mov_b32 m0, s70
	s_add_u32 s26, s28, 0x40080
	global_load_lds_dwordx4 v[8:9], off
	v_lshl_add_u64 v[8:9], v[14:15], 0, s[24:25]
	s_mov_b32 m0, s71
	s_addc_u32 s27, s29, 0
	s_add_i32 s52, s58, 0x1c000
	global_load_lds_dwordx4 v[8:9], off
	v_lshl_add_u64 v[8:9], s[26:27], 0, v[134:135]
	s_mov_b32 m0, s52
	s_add_i32 s50, s58, 0x1e000
	global_load_lds_dwordx4 v[8:9], off
	v_lshl_add_u64 v[8:9], s[26:27], 0, v[138:139]
	s_mov_b32 m0, s50
	v_bfe_u32 v7, v0, 4, 2
	global_load_lds_dwordx4 v[8:9], off
	v_and_b32_e32 v140, 15, v0
	v_lshlrev_b32_e32 v142, 4, v7
	v_lshlrev_b32_e32 v0, 2, v0
	v_lshlrev_b32_e32 v8, 3, v7
	v_lshl_or_b32 v7, v140, 6, v142
	v_and_b32_e32 v0, 32, v0
	v_bitop3_b32 v141, v7, s20, v0 bitop3:0xde
	v_bitop3_b32 v143, v7, s23, v0 bitop3:0xde
	v_lshlrev_b32_e32 v0, 14, v1
	s_lshl_b32 s67, s22, 2
	v_and_b32_e32 v0, 0xffff8000, v0
	s_add_i32 s4, s67, 8
	v_lshl_add_u32 v0, v2, 11, v0
	v_and_b32_e32 v1, 1, v1
	v_writelane_b32 v255, s4, 47
	s_add_i32 s4, s67, 9
	v_lshl_or_b32 v0, v1, 6, v0
	v_writelane_b32 v255, s4, 49
	s_add_i32 s4, s67, 10
	v_lshl_add_u32 v148, v3, 1, v0
	v_lshlrev_b32_e32 v0, 14, v4
	v_writelane_b32 v255, s4, 50
	s_add_i32 s4, s67, 11
	v_and_b32_e32 v0, 0xffff8000, v0
	s_waitcnt vmcnt(6)
	v_lshl_or_b32 v144, s49, 5, v8
	v_writelane_b32 v255, s4, 51
	v_readlane_b32 s4, v253, 16
	v_lshl_add_u32 v0, v5, 11, v0
	v_and_b32_e32 v1, 1, v4
	v_lshlrev_b32_e32 v184, 1, v144
	v_readlane_b32 s12, v253, 24
	v_readlane_b32 s13, v253, 25
	v_lshl_or_b32 v0, v1, 6, v0
	s_or_b32 s48, s49, 0xffffffc0
	v_mov_b32_e32 v145, v185
	s_or_b32 s84, s67, 1
	s_or_b32 s85, s67, 2
	s_or_b32 s92, s67, 3
	v_or_b32_e32 v156, 0x80, v144
	s_orn2_b32 s49, s49, 59
	v_lshl_add_u64 v[146:147], s[12:13], 0, v[184:185]
	v_mov_b32_e32 v149, v185
	v_lshl_add_u32 v150, v6, 1, v0
	v_mov_b32_e32 v151, v185
	s_mov_b32 s65, 0
	s_barrier
	v_readlane_b32 s5, v253, 17
	v_readlane_b32 s6, v253, 18
	v_readlane_b32 s7, v253, 19
	v_readlane_b32 s8, v253, 20
	v_readlane_b32 s9, v253, 21
	v_readlane_b32 s10, v253, 22
	v_readlane_b32 s11, v253, 23
	v_readlane_b32 s14, v253, 26
	v_readlane_b32 s15, v253, 27
	v_readlane_b32 s16, v253, 28
	v_readlane_b32 s17, v253, 29
	v_readlane_b32 s18, v253, 30
	v_readlane_b32 s19, v253, 31
	s_branch .LBB0_289

.LBB0_298:
	s_lshl_b32 s20, s55, 8
	s_addk_i32 s20, 0x1800
	s_cmp_eq_u32 s54, 0
	v_readlane_b32 s4, v253, 16
	s_cselect_b32 s26, s55, s20
	v_readlane_b32 s6, v253, 18
	v_readlane_b32 s7, v253, 19
	s_cselect_b32 s20, 19, 11
	s_cselect_b32 s34, s7, s57
	s_cselect_b32 s35, s6, s56
	s_cselect_b32 s36, s56, s6
	s_cselect_b32 s37, s57, s7
	s_ashr_i32 s27, s26, 31
	s_lshl_b64 s[26:27], s[26:27], s20
	s_add_u32 s42, s35, s26
	s_addc_u32 s43, s34, s27
	s_and_b64 s[26:27], s[30:31], exec
	s_cselect_b32 s20, s43, s1
	s_cselect_b32 s34, s42, s0
	s_ashr_i32 s41, s40, 31
	s_lshl_b64 s[26:27], s[40:41], 19
	s_add_u32 s44, s36, s26
	s_addc_u32 s45, s37, s27
	s_and_b64 s[26:27], s[30:31], exec
	s_cselect_b32 s35, s45, s29
	s_cselect_b32 s36, s44, s28
	s_add_u32 s0, s0, 0x40080
	s_addc_u32 s1, s1, 0
	s_add_u32 s37, s28, 0x100
	v_mov_b32_e32 v0, 0
	s_addc_u32 s26, s29, 0
	s_mov_b32 s27, -2
	v_mov_b32_e32 v1, v0
	v_mov_b32_e32 v2, v0
	v_mov_b32_e32 v3, v0
	v_mov_b32_e32 v4, v0
	v_mov_b32_e32 v5, v0
	v_mov_b32_e32 v6, v0
	v_mov_b32_e32 v7, v0
	v_mov_b32_e32 v8, v0
	v_mov_b32_e32 v9, v0
	v_mov_b32_e32 v10, v0
	v_mov_b32_e32 v11, v0
	v_mov_b32_e32 v12, v0
	v_mov_b32_e32 v13, v0
	v_mov_b32_e32 v14, v0
	v_mov_b32_e32 v15, v0
	v_mov_b32_e32 v16, v0
	v_mov_b32_e32 v17, v0
	v_mov_b32_e32 v18, v0
	v_mov_b32_e32 v19, v0
	v_mov_b32_e32 v20, v0
	v_mov_b32_e32 v21, v0
	v_mov_b32_e32 v22, v0
	v_mov_b32_e32 v23, v0
	v_mov_b32_e32 v24, v0
	v_mov_b32_e32 v25, v0
	v_mov_b32_e32 v26, v0
	v_mov_b32_e32 v27, v0
	v_mov_b32_e32 v28, v0
	v_mov_b32_e32 v29, v0
	v_mov_b32_e32 v30, v0
	v_mov_b32_e32 v31, v0
	v_mov_b32_e32 v32, v0
	v_mov_b32_e32 v33, v0
	v_mov_b32_e32 v34, v0
	v_mov_b32_e32 v35, v0
	v_mov_b32_e32 v36, v0
	v_mov_b32_e32 v37, v0
	v_mov_b32_e32 v38, v0
	v_mov_b32_e32 v39, v0
	v_mov_b32_e32 v40, v0
	v_mov_b32_e32 v41, v0
	v_mov_b32_e32 v42, v0
	v_mov_b32_e32 v43, v0
	v_mov_b32_e32 v44, v0
	v_mov_b32_e32 v45, v0
	v_mov_b32_e32 v46, v0
	v_mov_b32_e32 v47, v0
	v_mov_b32_e32 v48, v0
	v_mov_b32_e32 v49, v0
	v_mov_b32_e32 v50, v0
	v_mov_b32_e32 v51, v0
	v_mov_b32_e32 v52, v0
	v_mov_b32_e32 v53, v0
	v_mov_b32_e32 v54, v0
	v_mov_b32_e32 v55, v0
	v_mov_b32_e32 v56, v0
	v_mov_b32_e32 v57, v0
	v_mov_b32_e32 v58, v0
	v_mov_b32_e32 v59, v0
	v_mov_b32_e32 v60, v0
	v_mov_b32_e32 v61, v0
	v_mov_b32_e32 v62, v0
	v_mov_b32_e32 v63, v0
	v_mov_b32_e32 v64, v0
	v_mov_b32_e32 v65, v0
	v_mov_b32_e32 v66, v0
	v_mov_b32_e32 v67, v0
	v_mov_b32_e32 v68, v0
	v_mov_b32_e32 v69, v0
	v_mov_b32_e32 v70, v0
	v_mov_b32_e32 v71, v0
	v_mov_b32_e32 v72, v0
	v_mov_b32_e32 v73, v0
	v_mov_b32_e32 v74, v0
	v_mov_b32_e32 v75, v0
	v_mov_b32_e32 v76, v0
	v_mov_b32_e32 v77, v0
	v_mov_b32_e32 v78, v0
	v_mov_b32_e32 v79, v0
	v_mov_b32_e32 v80, v0
	v_mov_b32_e32 v81, v0
	v_mov_b32_e32 v82, v0
	v_mov_b32_e32 v83, v0
	v_mov_b32_e32 v84, v0
	v_mov_b32_e32 v85, v0
	v_mov_b32_e32 v86, v0
	v_mov_b32_e32 v87, v0
	v_mov_b32_e32 v88, v0
	v_mov_b32_e32 v89, v0
	v_mov_b32_e32 v90, v0
	v_mov_b32_e32 v91, v0
	v_mov_b32_e32 v92, v0
	v_mov_b32_e32 v93, v0
	v_mov_b32_e32 v94, v0
	v_mov_b32_e32 v95, v0
	v_mov_b32_e32 v96, v0
	v_mov_b32_e32 v97, v0
	v_mov_b32_e32 v98, v0
	v_mov_b32_e32 v99, v0
	v_mov_b32_e32 v100, v0
	v_mov_b32_e32 v101, v0
	v_mov_b32_e32 v102, v0
	v_mov_b32_e32 v103, v0
	v_mov_b32_e32 v104, v0
	v_mov_b32_e32 v105, v0
	v_mov_b32_e32 v106, v0
	v_mov_b32_e32 v107, v0
	v_mov_b32_e32 v108, v0
	v_mov_b32_e32 v109, v0
	v_mov_b32_e32 v110, v0
	v_mov_b32_e32 v111, v0
	v_mov_b32_e32 v112, v0
	v_mov_b32_e32 v113, v0
	v_mov_b32_e32 v114, v0
	v_mov_b32_e32 v115, v0
	v_mov_b32_e32 v116, v0
	v_mov_b32_e32 v117, v0
	v_mov_b32_e32 v118, v0
	v_mov_b32_e32 v119, v0
	v_mov_b32_e32 v120, v0
	v_mov_b32_e32 v121, v0
	v_mov_b32_e32 v122, v0
	v_mov_b32_e32 v123, v0
	v_mov_b32_e32 v124, v0
	v_mov_b32_e32 v125, v0
	v_mov_b32_e32 v126, v0
	v_mov_b32_e32 v127, v0
	v_readlane_b32 s5, v253, 17
	v_readlane_b32 s8, v253, 20
	v_readlane_b32 s9, v253, 21
	v_readlane_b32 s10, v253, 22
	v_readlane_b32 s11, v253, 23
	v_readlane_b32 s12, v253, 24
	v_readlane_b32 s13, v253, 25
	v_readlane_b32 s14, v253, 26
	v_readlane_b32 s15, v253, 27
	v_readlane_b32 s16, v253, 28
	v_readlane_b32 s17, v253, 29
	v_readlane_b32 s18, v253, 30
	v_readlane_b32 s19, v253, 31
	v_add_u32_e32 v230, 0x10000, v143
.LBB0_299:
	ds_read_b128 v[128:131], v230
	ds_read_b128 v[152:155], v230 offset:1024
	ds_read_b128 v[158:161], v230 offset:2048
	ds_read_b128 v[162:165], v230 offset:3072
	s_add_u32 s28, s0, 0xfffc0080
	s_addc_u32 s29, s1, -1
	s_cmp_eq_u32 s27, 12
	s_cselect_b32 s31, s20, s29
	s_cselect_b32 s30, s34, s28
	s_cselect_b32 s29, s35, s26
	s_cselect_b32 s28, s36, s37
	v_lshl_add_u64 v[182:183], s[0:1], 0, v[148:149]
	s_add_i32 m0, s58, 0xc000
	ds_read_b128 v[166:169], v141
	ds_read_b128 v[170:173], v141 offset:1024
	ds_read_b128 v[174:177], v141 offset:2048
	ds_read_b128 v[178:181], v141 offset:3072
	ds_read_b128 v[186:189], v141 offset:4096
	ds_read_b128 v[194:197], v141 offset:5120
	ds_read_b128 v[198:201], v141 offset:6144
	ds_read_b128 v[202:205], v141 offset:7168
	global_load_lds_dwordx4 v[182:183], off
	v_lshl_add_u64 v[182:183], s[0:1], 0, v[150:151]
	s_add_i32 m0, s58, 0xe000
	s_nop 0
	global_load_lds_dwordx4 v[182:183], off
	ds_read_b128 v[206:209], v230 offset:16384
	ds_read_b128 v[210:213], v230 offset:17408
	ds_read_b128 v[214:217], v230 offset:18432
	ds_read_b128 v[242:245], v230 offset:19456
	s_waitcnt vmcnt(8) lgkmcnt(0)
	s_barrier
	v_mfma_f32_16x16x32_bf16 v[124:127], v[128:131], v[166:169], v[124:127]
	v_mfma_f32_16x16x32_bf16 v[120:123], v[158:161], v[166:169], v[120:123]
	v_mfma_f32_16x16x32_bf16 v[116:119], v[128:131], v[174:177], v[116:119]
	v_mfma_f32_16x16x32_bf16 v[112:115], v[158:161], v[174:177], v[112:115]
	v_mfma_f32_16x16x32_bf16 v[108:111], v[128:131], v[186:189], v[108:111]
	v_mfma_f32_16x16x32_bf16 v[104:107], v[158:161], v[186:189], v[104:107]
	v_mfma_f32_16x16x32_bf16 v[100:103], v[128:131], v[198:201], v[100:103]
	v_mfma_f32_16x16x32_bf16 v[96:99], v[158:161], v[198:201], v[96:99]
	v_mfma_f32_16x16x32_bf16 v[124:127], v[152:155], v[170:173], v[124:127]
	v_mfma_f32_16x16x32_bf16 v[120:123], v[162:165], v[170:173], v[120:123]
	v_mfma_f32_16x16x32_bf16 v[116:119], v[152:155], v[178:181], v[116:119]
	v_mfma_f32_16x16x32_bf16 v[112:115], v[162:165], v[178:181], v[112:115]
	v_mfma_f32_16x16x32_bf16 v[108:111], v[152:155], v[194:197], v[108:111]
	v_mfma_f32_16x16x32_bf16 v[104:107], v[162:165], v[194:197], v[104:107]
	v_mfma_f32_16x16x32_bf16 v[100:103], v[152:155], v[202:205], v[100:103]
	v_mfma_f32_16x16x32_bf16 v[96:99], v[162:165], v[202:205], v[96:99]
	v_mfma_f32_16x16x32_bf16 v[92:95], v[206:209], v[166:169], v[92:95]
	v_mfma_f32_16x16x32_bf16 v[88:91], v[214:217], v[166:169], v[88:91]
	v_mfma_f32_16x16x32_bf16 v[84:87], v[206:209], v[174:177], v[84:87]
	v_mfma_f32_16x16x32_bf16 v[80:83], v[214:217], v[174:177], v[80:83]
	v_mfma_f32_16x16x32_bf16 v[76:79], v[206:209], v[186:189], v[76:79]
	v_mfma_f32_16x16x32_bf16 v[72:75], v[214:217], v[186:189], v[72:75]
	v_mfma_f32_16x16x32_bf16 v[68:71], v[206:209], v[198:201], v[68:71]
	v_mfma_f32_16x16x32_bf16 v[64:67], v[214:217], v[198:201], v[64:67]
	v_mfma_f32_16x16x32_bf16 v[92:95], v[210:213], v[170:173], v[92:95]
	v_mfma_f32_16x16x32_bf16 v[88:91], v[242:245], v[170:173], v[88:91]
	v_mfma_f32_16x16x32_bf16 v[84:87], v[210:213], v[178:181], v[84:87]
	v_mfma_f32_16x16x32_bf16 v[80:83], v[242:245], v[178:181], v[80:83]
	v_mfma_f32_16x16x32_bf16 v[76:79], v[210:213], v[194:197], v[76:79]
	v_mfma_f32_16x16x32_bf16 v[72:75], v[242:245], v[194:197], v[72:75]
	v_mfma_f32_16x16x32_bf16 v[68:71], v[210:213], v[202:205], v[68:71]
	v_mfma_f32_16x16x32_bf16 v[64:67], v[242:245], v[202:205], v[64:67]
	s_barrier
	s_mov_b32 m0, s39
	v_lshl_add_u64 v[182:183], s[28:29], 0, v[134:135]
	global_load_lds_dwordx4 v[182:183], off
	v_lshl_add_u64 v[190:191], s[28:29], 0, v[138:139]
	s_mov_b32 m0, s59
	s_nop 0
	global_load_lds_dwordx4 v[190:191], off
	s_mov_b32 m0, s58
	v_lshl_add_u64 v[246:247], s[30:31], 0, v[132:133]
	ds_read_b128 v[166:169], v141 offset:16384
	ds_read_b128 v[170:173], v141 offset:17408
	ds_read_b128 v[174:177], v141 offset:18432
	ds_read_b128 v[178:181], v141 offset:19456
	ds_read_b128 v[186:189], v141 offset:20480
	ds_read_b128 v[194:197], v141 offset:21504
	ds_read_b128 v[198:201], v141 offset:22528
	ds_read_b128 v[202:205], v141 offset:23552
	global_load_lds_dwordx4 v[246:247], off
	v_lshl_add_u64 v[248:249], s[30:31], 0, v[136:137]
	s_mov_b32 m0, s60
	s_nop 0
	global_load_lds_dwordx4 v[248:249], off
	s_waitcnt vmcnt(6) lgkmcnt(0)
	s_barrier
	v_mfma_f32_16x16x32_bf16 v[60:63], v[128:131], v[166:169], v[60:63]
	v_mfma_f32_16x16x32_bf16 v[56:59], v[158:161], v[166:169], v[56:59]
	v_mfma_f32_16x16x32_bf16 v[52:55], v[128:131], v[174:177], v[52:55]
	v_mfma_f32_16x16x32_bf16 v[48:51], v[158:161], v[174:177], v[48:51]
	v_mfma_f32_16x16x32_bf16 v[44:47], v[128:131], v[186:189], v[44:47]
	v_mfma_f32_16x16x32_bf16 v[40:43], v[158:161], v[186:189], v[40:43]
	v_mfma_f32_16x16x32_bf16 v[36:39], v[128:131], v[198:201], v[36:39]
	v_mfma_f32_16x16x32_bf16 v[32:35], v[158:161], v[198:201], v[32:35]
	v_mfma_f32_16x16x32_bf16 v[60:63], v[152:155], v[170:173], v[60:63]
	v_mfma_f32_16x16x32_bf16 v[56:59], v[162:165], v[170:173], v[56:59]
	v_mfma_f32_16x16x32_bf16 v[52:55], v[152:155], v[178:181], v[52:55]
	v_mfma_f32_16x16x32_bf16 v[48:51], v[162:165], v[178:181], v[48:51]
	v_mfma_f32_16x16x32_bf16 v[44:47], v[152:155], v[194:197], v[44:47]
	v_mfma_f32_16x16x32_bf16 v[40:43], v[162:165], v[194:197], v[40:43]
	v_mfma_f32_16x16x32_bf16 v[36:39], v[152:155], v[202:205], v[36:39]
	v_mfma_f32_16x16x32_bf16 v[32:35], v[162:165], v[202:205], v[32:35]
	v_mfma_f32_16x16x32_bf16 v[28:31], v[206:209], v[166:169], v[28:31]
	v_mfma_f32_16x16x32_bf16 v[24:27], v[214:217], v[166:169], v[24:27]
	v_mfma_f32_16x16x32_bf16 v[20:23], v[206:209], v[174:177], v[20:23]
	v_mfma_f32_16x16x32_bf16 v[16:19], v[214:217], v[174:177], v[16:19]
	v_mfma_f32_16x16x32_bf16 v[12:15], v[206:209], v[186:189], v[12:15]
	v_mfma_f32_16x16x32_bf16 v[8:11], v[214:217], v[186:189], v[8:11]
	v_mfma_f32_16x16x32_bf16 v[4:7], v[206:209], v[198:201], v[4:7]
	v_mfma_f32_16x16x32_bf16 v[0:3], v[214:217], v[198:201], v[0:3]
	v_mfma_f32_16x16x32_bf16 v[28:31], v[210:213], v[170:173], v[28:31]
	v_mfma_f32_16x16x32_bf16 v[24:27], v[242:245], v[170:173], v[24:27]
	v_mfma_f32_16x16x32_bf16 v[20:23], v[210:213], v[178:181], v[20:23]
	v_mfma_f32_16x16x32_bf16 v[16:19], v[242:245], v[178:181], v[16:19]
	v_mfma_f32_16x16x32_bf16 v[12:15], v[210:213], v[194:197], v[12:15]
	v_mfma_f32_16x16x32_bf16 v[8:11], v[242:245], v[194:197], v[8:11]
	v_mfma_f32_16x16x32_bf16 v[4:7], v[210:213], v[202:205], v[4:7]
	v_mfma_f32_16x16x32_bf16 v[0:3], v[242:245], v[202:205], v[0:3]
	s_barrier
	s_add_u32 s46, s28, 0x40000
	s_addc_u32 s47, s29, 0
	s_mov_b32 m0, s61
	v_lshl_add_u64 v[128:129], s[46:47], 0, v[134:135]
	global_load_lds_dwordx4 v[128:129], off
	v_lshl_add_u64 v[128:129], s[46:47], 0, v[138:139]
	s_mov_b32 m0, s62
	s_nop 0
	global_load_lds_dwordx4 v[128:129], off
	ds_read_b128 v[128:131], v230 offset:32768
	ds_read_b128 v[152:155], v230 offset:33792
	ds_read_b128 v[158:161], v230 offset:34816
	ds_read_b128 v[162:165], v230 offset:35840
	s_add_u32 s30, s30, 0x40000
	s_addc_u32 s31, s31, 0
	s_mov_b32 m0, s63
	v_lshl_add_u64 v[206:207], s[30:31], 0, v[132:133]
	ds_read_b128 v[166:169], v141 offset:32768
	ds_read_b128 v[170:173], v141 offset:33792
	ds_read_b128 v[174:177], v141 offset:34816
	ds_read_b128 v[178:181], v141 offset:35840
	ds_read_b128 v[186:189], v141 offset:36864
	ds_read_b128 v[194:197], v141 offset:37888
	ds_read_b128 v[198:201], v141 offset:38912
	ds_read_b128 v[202:205], v141 offset:39936
	global_load_lds_dwordx4 v[206:207], off
	v_lshl_add_u64 v[206:207], s[30:31], 0, v[136:137]
	s_mov_b32 m0, s64
	s_nop 0
	global_load_lds_dwordx4 v[206:207], off
	ds_read_b128 v[206:209], v230 offset:49152
	ds_read_b128 v[210:213], v230 offset:50176
	ds_read_b128 v[214:217], v230 offset:51200
	ds_read_b128 v[242:245], v230 offset:52224
	s_waitcnt vmcnt(8) lgkmcnt(0)
	s_barrier
	v_mfma_f32_16x16x32_bf16 v[124:127], v[128:131], v[166:169], v[124:127]
	v_mfma_f32_16x16x32_bf16 v[120:123], v[158:161], v[166:169], v[120:123]
	v_mfma_f32_16x16x32_bf16 v[116:119], v[128:131], v[174:177], v[116:119]
	v_mfma_f32_16x16x32_bf16 v[112:115], v[158:161], v[174:177], v[112:115]
	v_mfma_f32_16x16x32_bf16 v[108:111], v[128:131], v[186:189], v[108:111]
	v_mfma_f32_16x16x32_bf16 v[104:107], v[158:161], v[186:189], v[104:107]
	v_mfma_f32_16x16x32_bf16 v[100:103], v[128:131], v[198:201], v[100:103]
	v_mfma_f32_16x16x32_bf16 v[96:99], v[158:161], v[198:201], v[96:99]
	v_mfma_f32_16x16x32_bf16 v[124:127], v[152:155], v[170:173], v[124:127]
	v_mfma_f32_16x16x32_bf16 v[120:123], v[162:165], v[170:173], v[120:123]
	v_mfma_f32_16x16x32_bf16 v[116:119], v[152:155], v[178:181], v[116:119]
	v_mfma_f32_16x16x32_bf16 v[112:115], v[162:165], v[178:181], v[112:115]
	v_mfma_f32_16x16x32_bf16 v[108:111], v[152:155], v[194:197], v[108:111]
	v_mfma_f32_16x16x32_bf16 v[104:107], v[162:165], v[194:197], v[104:107]
	v_mfma_f32_16x16x32_bf16 v[100:103], v[152:155], v[202:205], v[100:103]
	v_mfma_f32_16x16x32_bf16 v[96:99], v[162:165], v[202:205], v[96:99]
	v_mfma_f32_16x16x32_bf16 v[92:95], v[206:209], v[166:169], v[92:95]
	v_mfma_f32_16x16x32_bf16 v[88:91], v[214:217], v[166:169], v[88:91]
	v_mfma_f32_16x16x32_bf16 v[84:87], v[206:209], v[174:177], v[84:87]
	v_mfma_f32_16x16x32_bf16 v[80:83], v[214:217], v[174:177], v[80:83]
	v_mfma_f32_16x16x32_bf16 v[76:79], v[206:209], v[186:189], v[76:79]
	v_mfma_f32_16x16x32_bf16 v[72:75], v[214:217], v[186:189], v[72:75]
	v_mfma_f32_16x16x32_bf16 v[68:71], v[206:209], v[198:201], v[68:71]
	v_mfma_f32_16x16x32_bf16 v[64:67], v[214:217], v[198:201], v[64:67]
	v_mfma_f32_16x16x32_bf16 v[92:95], v[210:213], v[170:173], v[92:95]
	v_mfma_f32_16x16x32_bf16 v[88:91], v[242:245], v[170:173], v[88:91]
	v_mfma_f32_16x16x32_bf16 v[84:87], v[210:213], v[178:181], v[84:87]
	v_mfma_f32_16x16x32_bf16 v[80:83], v[242:245], v[178:181], v[80:83]
	v_mfma_f32_16x16x32_bf16 v[76:79], v[210:213], v[194:197], v[76:79]
	v_mfma_f32_16x16x32_bf16 v[72:75], v[242:245], v[194:197], v[72:75]
	v_mfma_f32_16x16x32_bf16 v[68:71], v[210:213], v[202:205], v[68:71]
	v_mfma_f32_16x16x32_bf16 v[64:67], v[242:245], v[202:205], v[64:67]
	s_barrier
	s_mov_b32 m0, s68
	v_lshl_add_u64 v[182:183], v[182:183], 0, s[24:25]
	global_load_lds_dwordx4 v[182:183], off
	v_lshl_add_u64 v[182:183], v[190:191], 0, s[24:25]
	s_mov_b32 m0, s69
	s_nop 0
	global_load_lds_dwordx4 v[182:183], off
	s_mov_b32 m0, s70
	v_lshl_add_u64 v[182:183], v[246:247], 0, s[24:25]
	ds_read_b128 v[166:169], v141 offset:49152
	ds_read_b128 v[170:173], v141 offset:50176
	ds_read_b128 v[174:177], v141 offset:51200
	ds_read_b128 v[178:181], v141 offset:52224
	ds_read_b128 v[186:189], v141 offset:53248
	ds_read_b128 v[194:197], v141 offset:54272
	ds_read_b128 v[198:201], v141 offset:55296
	ds_read_b128 v[202:205], v141 offset:56320
	global_load_lds_dwordx4 v[182:183], off
	v_lshl_add_u64 v[182:183], v[248:249], 0, s[24:25]
	s_mov_b32 m0, s71
	s_nop 0
	global_load_lds_dwordx4 v[182:183], off
	s_waitcnt vmcnt(6) lgkmcnt(0)
	s_barrier
	v_mfma_f32_16x16x32_bf16 v[60:63], v[128:131], v[166:169], v[60:63]
	v_mfma_f32_16x16x32_bf16 v[56:59], v[158:161], v[166:169], v[56:59]
	v_mfma_f32_16x16x32_bf16 v[52:55], v[128:131], v[174:177], v[52:55]
	v_mfma_f32_16x16x32_bf16 v[48:51], v[158:161], v[174:177], v[48:51]
	v_mfma_f32_16x16x32_bf16 v[44:47], v[128:131], v[186:189], v[44:47]
	v_mfma_f32_16x16x32_bf16 v[40:43], v[158:161], v[186:189], v[40:43]
	v_mfma_f32_16x16x32_bf16 v[36:39], v[128:131], v[198:201], v[36:39]
	v_mfma_f32_16x16x32_bf16 v[32:35], v[158:161], v[198:201], v[32:35]
	v_mfma_f32_16x16x32_bf16 v[60:63], v[152:155], v[170:173], v[60:63]
	v_mfma_f32_16x16x32_bf16 v[56:59], v[162:165], v[170:173], v[56:59]
	v_mfma_f32_16x16x32_bf16 v[52:55], v[152:155], v[178:181], v[52:55]
	v_mfma_f32_16x16x32_bf16 v[48:51], v[162:165], v[178:181], v[48:51]
	v_mfma_f32_16x16x32_bf16 v[44:47], v[152:155], v[194:197], v[44:47]
	v_mfma_f32_16x16x32_bf16 v[40:43], v[162:165], v[194:197], v[40:43]
	v_mfma_f32_16x16x32_bf16 v[36:39], v[152:155], v[202:205], v[36:39]
	v_mfma_f32_16x16x32_bf16 v[32:35], v[162:165], v[202:205], v[32:35]
	v_mfma_f32_16x16x32_bf16 v[28:31], v[206:209], v[166:169], v[28:31]
	v_mfma_f32_16x16x32_bf16 v[24:27], v[214:217], v[166:169], v[24:27]
	v_mfma_f32_16x16x32_bf16 v[20:23], v[206:209], v[174:177], v[20:23]
	v_mfma_f32_16x16x32_bf16 v[16:19], v[214:217], v[174:177], v[16:19]
	v_mfma_f32_16x16x32_bf16 v[12:15], v[206:209], v[186:189], v[12:15]
	v_mfma_f32_16x16x32_bf16 v[8:11], v[214:217], v[186:189], v[8:11]
	v_mfma_f32_16x16x32_bf16 v[4:7], v[206:209], v[198:201], v[4:7]
	v_mfma_f32_16x16x32_bf16 v[0:3], v[214:217], v[198:201], v[0:3]
	v_mfma_f32_16x16x32_bf16 v[28:31], v[210:213], v[170:173], v[28:31]
	v_mfma_f32_16x16x32_bf16 v[24:27], v[242:245], v[170:173], v[24:27]
	v_mfma_f32_16x16x32_bf16 v[20:23], v[210:213], v[178:181], v[20:23]
	v_mfma_f32_16x16x32_bf16 v[16:19], v[242:245], v[178:181], v[16:19]
	v_mfma_f32_16x16x32_bf16 v[12:15], v[210:213], v[194:197], v[12:15]
	v_mfma_f32_16x16x32_bf16 v[8:11], v[242:245], v[194:197], v[8:11]
	v_mfma_f32_16x16x32_bf16 v[4:7], v[210:213], v[202:205], v[4:7]
	v_mfma_f32_16x16x32_bf16 v[0:3], v[242:245], v[202:205], v[0:3]
	s_barrier
	s_add_u32 s28, s28, 0x40080
	s_addc_u32 s29, s29, 0
	s_mov_b32 m0, s52
	v_lshl_add_u64 v[128:129], s[28:29], 0, v[134:135]
	global_load_lds_dwordx4 v[128:129], off
	v_lshl_add_u64 v[128:129], s[28:29], 0, v[138:139]
	s_mov_b32 m0, s50
	s_nop 0
	global_load_lds_dwordx4 v[128:129], off
	s_add_i32 s27, s27, 2
	s_add_u32 s0, s0, 0x100
	s_addc_u32 s1, s1, 0
	s_add_u32 s37, s37, 0x100
	s_addc_u32 s26, s26, 0
	s_cmp_gt_u32 s27, 13
	s_cbranch_scc0 .LBB0_299
	s_lshl_b32 s20, s53, 8
	s_add_i32 s20, s20, s66
	s_lshl_b32 s46, s38, 8
	s_cmp_lg_u32 s33, 0
	v_or_b32_e32 v154, s20, v140
	v_or_b32_e32 v152, s46, v144
	s_cselect_b64 s[28:29], -1, 0
	s_movk_i32 s33, 0x3fff
	s_and_b64 vcc, exec, s[28:29]
	v_and_b32_e32 v157, 0xcf, v154
	v_cmp_lt_i32_e64 s[0:1], s33, v152
	s_cbranch_vccz .LBB0_306
	s_ashr_i32 s30, s20, 8
	v_cvt_pk_bf16_f32 v128, v124, v125
	v_cvt_pk_bf16_f32 v129, v126, v127
	v_cvt_pk_bf16_f32 v130, v120, v121
	v_cvt_pk_bf16_f32 v131, v122, v123
	s_and_saveexec_b64 s[26:27], s[0:1]
	s_xor_b64 s[0:1], exec, s[26:27]
	s_cbranch_execz .LBB0_303
	s_add_i32 s26, s46, 0xffffc000
	s_lshr_b32 s26, s26, 7
	v_lshl_add_u32 v184, v157, 4, s26
	s_ashr_i32 s31, s30, 31
	v_lshl_add_u64 v[158:159], v[184:185], 0, s[30:31]
	v_lshlrev_b64 v[158:159], 9, v[158:159]
	v_lshl_add_u64 v[158:159], v[146:147], 0, v[158:159]
	global_store_dwordx4 v[158:159], v[128:131], off
